# baseline (speedup 1.0000x reference)
; template <int DH, int MODE>
; __device__ void attn_item(const Params& p, int layer, int b, int blk, int head, char* smem) {
;     ...
;     __syncthreads();
;     V_SCATTER_(vr0, 0);
;     V_SCATTER_(vr1, 1);
;     if (KCH > 2) {
;       V_SCATTER_(vr2, 2);
;       V_SCATTER_(vr3, 3);
;     }
;     KV_LOAD_(it + 1);
;     if (!wskip) {
;       float4* s4 = reinterpret_cast<float4*>(Sf + row * SSTR + half * 32);
;       char* prow = Pb + half * 8192 + row * 64;
;       if (MODE == 0) {
;         const int kjb = kj0 + half * 32;
;         float tmax = -1e30f;
; #pragma unroll
;         for (int c = 0; c < 8; ++c) {
;           float4 v = s4[c];
;           float e[4] = {v.x, v.y, v.z, v.w};
; #pragma unroll
;           for (int k = 0; k < 4; ++k) {
;             int kj = kjb + c * 4 + k;
;             bool valid = (kj > row) && (kj <= row + 128);
;             tmax = valid ? fmaxf(tmax, e[k]) : tmax;
;           }
;         }
.LBB0_166:
	s_or_b64 exec, exec, s[6:7]
	s_add_i32 s86, s86, 1
	s_min_i32 s6, s86, s84
	s_add_i32 s6, s6, s83
	s_lshl_b32 s6, s6, 6
	s_add_i32 s6, s6, s85
	s_ashr_i32 s7, s6, 31
	s_add_u32 s6, s6, s81
	s_addc_u32 s7, s7, 0
	s_waitcnt lgkmcnt(0)
	s_barrier
	ds_write_b16 v96, v48
	ds_write_b16_d16_hi v96, v48 offset:64
	ds_write_b16 v96, v49 offset:128
	ds_write_b16_d16_hi v96, v49 offset:192
	ds_write_b16 v96, v50 offset:256
	ds_write_b16_d16_hi v96, v50 offset:320
	ds_write_b16 v96, v51 offset:384
	ds_write_b16_d16_hi v96, v51 offset:448
	s_waitcnt vmcnt(0)
	ds_write_b16 v96, v52 offset:2048
	ds_write_b16_d16_hi v96, v52 offset:2112
	ds_write_b16 v96, v53 offset:2176
	ds_write_b16_d16_hi v96, v53 offset:2240
	ds_write_b16 v96, v54 offset:2304
	ds_write_b16_d16_hi v96, v54 offset:2368
	ds_write_b16 v96, v55 offset:2432
	ds_write_b16_d16_hi v96, v55 offset:2496
	v_lshl_add_u64 v[48:49], s[6:7], 0, v[66:67]
	v_mad_u64_u32 v[52:53], s[10:11], v48, s55, v[76:77]
	v_or_b32_e32 v48, s6, v72
	v_mad_i32_i24 v53, v49, s55, v53
	v_mad_u64_u32 v[54:55], s[10:11], v48, s55, v[78:79]
	v_add_co_u32_e32 v48, vcc, 0x4c000, v52
	v_mad_i32_i24 v55, s7, v160, v55
	s_nop 0
	v_addc_co_u32_e32 v49, vcc, 0, v53, vcc
	global_load_dwordx4 v[60:63], v[48:49], off
	s_nop 0
	global_load_dwordx4 v[48:51], v[54:55], off
	global_load_dwordx4 v[56:59], v[52:53], off
	s_nop 0
	global_load_dwordx4 v[52:55], v[54:55], off offset:64
	s_and_saveexec_b64 s[52:53], s[50:51]
	s_cbranch_execz .LBB0_188
	v_or_b32_e32 v101, s8, v89
	s_movk_i32 s91, 0x80
	ds_read_b128 v[164:167], v90 offset:16384
	ds_read_b128 v[168:171], v90 offset:16400
	ds_read_b128 v[172:175], v90 offset:16416
	ds_read_b128 v[176:179], v90 offset:16432
	ds_read_b128 v[180:183], v90 offset:16448
	ds_read_b128 v[184:187], v90 offset:16464
	ds_read_b128 v[188:191], v90 offset:16480
	ds_read_b128 v[192:195], v90 offset:16496
	v_sub_u32_e32 v102, v80, v101
	v_mov_b32_e32 v83, 0xf149f2ca
	v_mov_b32_e32 v196, v102
	v_add_u32_e32 v197, -1, v102
	v_add_u32_e32 v198, -2, v102
	v_cmp_gt_u32_e32 vcc, s91, v196
	v_cmp_gt_u32_e64 s[92:93], s91, v197
	v_cmp_gt_u32_e64 s[94:95], s91, v198
	s_waitcnt lgkmcnt(7)
	v_cndmask_b32_e32 v164, v83, v164, vcc
	v_cndmask_b32_e64 v165, v83, v165, s[92:93]
	v_cndmask_b32_e64 v166, v83, v166, s[94:95]
	v_add_u32_e32 v196, -3, v102
	v_add_u32_e32 v197, -4, v102
	v_add_u32_e32 v198, -5, v102
	v_cmp_gt_u32_e32 vcc, s91, v196
	v_cmp_gt_u32_e64 s[92:93], s91, v197
	v_cmp_gt_u32_e64 s[94:95], s91, v198
	s_waitcnt lgkmcnt(6)
	v_cndmask_b32_e32 v167, v83, v167, vcc
	v_cndmask_b32_e64 v168, v83, v168, s[92:93]
	v_cndmask_b32_e64 v169, v83, v169, s[94:95]
	v_add_u32_e32 v196, -6, v102
	v_add_u32_e32 v197, -7, v102
	v_add_u32_e32 v198, -8, v102
	v_cmp_gt_u32_e32 vcc, s91, v196
	v_cmp_gt_u32_e64 s[92:93], s91, v197
	v_cmp_gt_u32_e64 s[94:95], s91, v198
	s_waitcnt lgkmcnt(5)
	v_cndmask_b32_e32 v170, v83, v170, vcc
	v_cndmask_b32_e64 v171, v83, v171, s[92:93]
	v_cndmask_b32_e64 v172, v83, v172, s[94:95]
	v_add_u32_e32 v196, -9, v102
	v_add_u32_e32 v197, -10, v102
	v_add_u32_e32 v198, -11, v102
	v_cmp_gt_u32_e32 vcc, s91, v196
	v_cmp_gt_u32_e64 s[92:93], s91, v197
	v_cmp_gt_u32_e64 s[94:95], s91, v198
	v_cndmask_b32_e32 v173, v83, v173, vcc
	v_cndmask_b32_e64 v174, v83, v174, s[92:93]
	v_cndmask_b32_e64 v175, v83, v175, s[94:95]
	v_add_u32_e32 v196, -12, v102
	v_add_u32_e32 v197, -13, v102
	v_add_u32_e32 v198, -14, v102
	v_cmp_gt_u32_e32 vcc, s91, v196
	v_cmp_gt_u32_e64 s[92:93], s91, v197
	v_cmp_gt_u32_e64 s[94:95], s91, v198
	s_waitcnt lgkmcnt(4)
	v_cndmask_b32_e32 v176, v83, v176, vcc
	v_cndmask_b32_e64 v177, v83, v177, s[92:93]
	v_cndmask_b32_e64 v178, v83, v178, s[94:95]
	v_add_u32_e32 v196, -15, v102
	v_add_u32_e32 v197, -16, v102
	v_add_u32_e32 v198, 0xffffffef, v102
	v_cmp_gt_u32_e32 vcc, s91, v196
	v_cmp_gt_u32_e64 s[92:93], s91, v197
	v_cmp_gt_u32_e64 s[94:95], s91, v198
	s_waitcnt lgkmcnt(3)
	v_cndmask_b32_e32 v179, v83, v179, vcc
	v_cndmask_b32_e64 v180, v83, v180, s[92:93]
	v_cndmask_b32_e64 v181, v83, v181, s[94:95]
	v_add_u32_e32 v196, 0xffffffee, v102
	v_add_u32_e32 v197, 0xffffffed, v102
	v_add_u32_e32 v198, 0xffffffec, v102
	v_cmp_gt_u32_e32 vcc, s91, v196
	v_cmp_gt_u32_e64 s[92:93], s91, v197
	v_cmp_gt_u32_e64 s[94:95], s91, v198
	s_waitcnt lgkmcnt(2)
	v_cndmask_b32_e32 v182, v83, v182, vcc
	v_cndmask_b32_e64 v183, v83, v183, s[92:93]
	v_cndmask_b32_e64 v184, v83, v184, s[94:95]
	v_add_u32_e32 v196, 0xffffffeb, v102
	v_add_u32_e32 v197, 0xffffffea, v102
	v_add_u32_e32 v198, 0xffffffe9, v102
	v_cmp_gt_u32_e32 vcc, s91, v196
	v_cmp_gt_u32_e64 s[92:93], s91, v197
	v_cmp_gt_u32_e64 s[94:95], s91, v198
	v_cndmask_b32_e32 v185, v83, v185, vcc
	v_cndmask_b32_e64 v186, v83, v186, s[92:93]
	v_cndmask_b32_e64 v187, v83, v187, s[94:95]
	v_add_u32_e32 v196, 0xffffffe8, v102
	v_add_u32_e32 v197, 0xffffffe7, v102
	v_add_u32_e32 v198, 0xffffffe6, v102
	v_cmp_gt_u32_e32 vcc, s91, v196
	v_cmp_gt_u32_e64 s[92:93], s91, v197
	v_cmp_gt_u32_e64 s[94:95], s91, v198
	s_waitcnt lgkmcnt(1)
	v_cndmask_b32_e32 v188, v83, v188, vcc
	v_cndmask_b32_e64 v189, v83, v189, s[92:93]
	v_cndmask_b32_e64 v190, v83, v190, s[94:95]
	v_add_u32_e32 v196, 0xffffffe5, v102
	v_add_u32_e32 v197, 0xffffffe4, v102
	v_add_u32_e32 v198, 0xffffffe3, v102
	v_cmp_gt_u32_e32 vcc, s91, v196
	v_cmp_gt_u32_e64 s[92:93], s91, v197
	v_cmp_gt_u32_e64 s[94:95], s91, v198
	s_waitcnt lgkmcnt(0)
; template <int DH, int MODE>
; __device__ void attn_item(const Params& p, int layer, int b, int blk, int head, char* smem) {
;     ...
; #pragma unroll
;         for (int c = 0; c < 8; ++c) {
;           float4 v = s4[c];
;           float e[4] = {v.x, v.y, v.z, v.w};
; #pragma unroll
;           for (int k = 0; k < 4; ++k) {
;             int kj = kjb + c * 4 + k;
;             bool valid = (kj > row) && (kj <= row + 128);
;             tmax = valid ? fmaxf(tmax, e[k]) : tmax;
;           }
;         }
;         tmax = fmaxf(tmax, __shfl_xor(tmax, 1));
;         float m_new = fmaxf(m_run, tmax);
;         float alpha = __builtin_amdgcn_exp2f(m_run - m_new);
;         float psum = 0.f;
; #pragma unroll 2
;         for (int s8 = 0; s8 < 4; ++s8) {
;           float4 va = s4[2 * s8], vb = s4[2 * s8 + 1];
;           float e[8] = {va.x, va.y, va.z, va.w, vb.x, vb.y, vb.z, vb.w};
;           float pv[8];
; #pragma unroll
;           for (int k = 0; k < 8; ++k) {
;             int kj = kjb + s8 * 8 + k;
;             bool valid = (kj > row) && (kj <= row + 128);
;             float pe = valid ? __builtin_amdgcn_exp2f(e[k] - m_new) : 0.f;
;             pv[k] = pe;
;             psum += pe;
;           }
	v_cndmask_b32_e32 v191, v83, v191, vcc
	v_cndmask_b32_e64 v192, v83, v192, s[92:93]
	v_cndmask_b32_e64 v193, v83, v193, s[94:95]
	v_add_u32_e32 v196, 0xffffffe2, v102
	v_add_u32_e32 v197, 0xffffffe1, v102
	v_cmp_gt_u32_e32 vcc, s91, v196
	v_cmp_gt_u32_e64 s[92:93], s91, v197
	s_nop 0
	v_cndmask_b32_e32 v194, v83, v194, vcc
	v_cndmask_b32_e64 v195, v83, v195, s[92:93]
	v_max3_f32 v164, v164, v165, v166
	v_max3_f32 v167, v167, v168, v169
	v_max3_f32 v170, v170, v171, v172
	v_max3_f32 v173, v173, v174, v175
	v_max3_f32 v176, v176, v177, v178
	v_max3_f32 v179, v179, v180, v181
	v_max3_f32 v182, v182, v183, v184
	v_max3_f32 v185, v185, v186, v187
	v_max3_f32 v188, v188, v189, v190
	v_max3_f32 v191, v191, v192, v193
	v_max_f32_e32 v194, v194, v195
	v_max3_f32 v164, v164, v167, v170
	v_max3_f32 v173, v173, v176, v179
	v_max3_f32 v182, v182, v185, v188
	v_max_f32_e32 v191, v191, v194
	v_max3_f32 v164, v164, v173, v182
	v_max_f32_e32 v164, v164, v191
	v_mov_b32_e32 v82, v164
	v_cmp_lt_i32_e32 vcc, v157, v158
	s_mov_b32 s87, 0
	v_mov_b32_e32 v103, 0
	v_cndmask_b32_e32 v83, v156, v157, vcc
	v_lshlrev_b32_e32 v83, 2, v83
	ds_bpermute_b32 v101, v83, v82
	v_mov_b32_e32 v102, v91
	s_waitcnt lgkmcnt(0)
	v_max3_f32 v82, v87, v82, v101
	v_mov_b32_e32 v101, v93
	ds_read_b128 v[164:167], v102
	ds_read_b128 v[168:171], v102 offset:16
	ds_read_b128 v[172:175], v102 offset:32
	ds_read_b128 v[176:179], v102 offset:48
	ds_read_b128 v[180:183], v102 offset:64
	ds_read_b128 v[184:187], v102 offset:80
	ds_read_b128 v[188:191], v102 offset:96
	ds_read_b128 v[192:195], v102 offset:112
	s_movk_i32 s91, 0x80
	v_sub_u32_e32 v112, v80, v92
	s_waitcnt lgkmcnt(7)
	v_sub_f32_e32 v164, v164, v82
	v_sub_f32_e32 v165, v165, v82
	v_sub_f32_e32 v166, v166, v82
	v_exp_f32_e32 v164, v164
	v_exp_f32_e32 v165, v165
	v_exp_f32_e32 v166, v166
	v_mov_b32_e32 v196, v112
	v_add_u32_e32 v197, -1, v112
	v_add_u32_e32 v198, -2, v112
	v_cmp_gt_u32_e32 vcc, s91, v196
	v_cmp_gt_u32_e64 s[92:93], s91, v197
	v_cmp_gt_u32_e64 s[94:95], s91, v198
	v_cndmask_b32_e32 v164, 0, v164, vcc
	v_cndmask_b32_e64 v165, 0, v165, s[92:93]
	v_cndmask_b32_e64 v166, 0, v166, s[94:95]
	v_add_f32_e32 v103, v103, v164
	v_add_f32_e32 v103, v103, v165
	v_add_f32_e32 v103, v103, v166
	s_waitcnt lgkmcnt(6)
	v_sub_f32_e32 v167, v167, v82
	v_sub_f32_e32 v168, v168, v82
	v_sub_f32_e32 v169, v169, v82
	v_exp_f32_e32 v167, v167
	v_exp_f32_e32 v168, v168
	v_exp_f32_e32 v169, v169
	v_add_u32_e32 v196, -3, v112
	v_add_u32_e32 v197, -4, v112
	v_add_u32_e32 v198, -5, v112
	v_cmp_gt_u32_e32 vcc, s91, v196
	v_cmp_gt_u32_e64 s[92:93], s91, v197
	v_cmp_gt_u32_e64 s[94:95], s91, v198
	v_cndmask_b32_e32 v167, 0, v167, vcc
	v_cndmask_b32_e64 v168, 0, v168, s[92:93]
	v_cndmask_b32_e64 v169, 0, v169, s[94:95]
	v_add_f32_e32 v103, v103, v167
	v_add_f32_e32 v103, v103, v168
	v_add_f32_e32 v103, v103, v169
	s_waitcnt lgkmcnt(5)
	v_sub_f32_e32 v170, v170, v82
	v_sub_f32_e32 v171, v171, v82
	v_sub_f32_e32 v172, v172, v82
	v_exp_f32_e32 v170, v170
	v_exp_f32_e32 v171, v171
	v_exp_f32_e32 v172, v172
	v_add_u32_e32 v196, -6, v112
	v_add_u32_e32 v197, -7, v112
	v_add_u32_e32 v198, -8, v112
	v_cmp_gt_u32_e32 vcc, s91, v196
	v_cmp_gt_u32_e64 s[92:93], s91, v197
	v_cmp_gt_u32_e64 s[94:95], s91, v198
	v_cndmask_b32_e32 v170, 0, v170, vcc
	v_cndmask_b32_e64 v171, 0, v171, s[92:93]
	v_cndmask_b32_e64 v172, 0, v172, s[94:95]
	v_add_f32_e32 v103, v103, v170
	v_add_f32_e32 v103, v103, v171
	v_add_f32_e32 v103, v103, v172
	v_sub_f32_e32 v173, v173, v82
	v_sub_f32_e32 v174, v174, v82
	v_sub_f32_e32 v175, v175, v82
	v_exp_f32_e32 v173, v173
	v_exp_f32_e32 v174, v174
	v_exp_f32_e32 v175, v175
	v_add_u32_e32 v196, -9, v112
	v_add_u32_e32 v197, -10, v112
	v_add_u32_e32 v198, -11, v112
	v_cmp_gt_u32_e32 vcc, s91, v196
	v_cmp_gt_u32_e64 s[92:93], s91, v197
	v_cmp_gt_u32_e64 s[94:95], s91, v198
	v_cndmask_b32_e32 v173, 0, v173, vcc
	v_cndmask_b32_e64 v174, 0, v174, s[92:93]
	v_cndmask_b32_e64 v175, 0, v175, s[94:95]
	v_add_f32_e32 v103, v103, v173
	v_add_f32_e32 v103, v103, v174
	v_add_f32_e32 v103, v103, v175
	s_waitcnt lgkmcnt(4)
	v_sub_f32_e32 v176, v176, v82
	v_sub_f32_e32 v177, v177, v82
	v_sub_f32_e32 v178, v178, v82
	v_exp_f32_e32 v176, v176
	v_exp_f32_e32 v177, v177
	v_exp_f32_e32 v178, v178
	v_add_u32_e32 v196, -12, v112
	v_add_u32_e32 v197, -13, v112
	v_add_u32_e32 v198, -14, v112
	v_cmp_gt_u32_e32 vcc, s91, v196
	v_cmp_gt_u32_e64 s[92:93], s91, v197
	v_cmp_gt_u32_e64 s[94:95], s91, v198
	v_cndmask_b32_e32 v176, 0, v176, vcc
	v_cndmask_b32_e64 v177, 0, v177, s[92:93]
	v_cndmask_b32_e64 v178, 0, v178, s[94:95]
	v_add_f32_e32 v103, v103, v176
	v_add_f32_e32 v103, v103, v177
	v_add_f32_e32 v103, v103, v178
	s_waitcnt lgkmcnt(3)
; __device__ __forceinline__ unsigned pack2(float a, float b) { return (unsigned)f2bf(a) | ((unsigned)f2bf(b) << 16); }
; template <int DH, int MODE>
; __device__ void attn_item(const Params& p, int layer, int b, int blk, int head, char* smem) {
;     ...
; #pragma unroll 2
;         for (int s8 = 0; s8 < 4; ++s8) {
;           float4 va = s4[2 * s8], vb = s4[2 * s8 + 1];
;           float e[8] = {va.x, va.y, va.z, va.w, vb.x, vb.y, vb.z, vb.w};
;           float pv[8];
; #pragma unroll
;           for (int k = 0; k < 8; ++k) {
;             int kj = kjb + s8 * 8 + k;
;             bool valid = (kj > row) && (kj <= row + 128);
;             float pe = valid ? __builtin_amdgcn_exp2f(e[k] - m_new) : 0.f;
;             pv[k] = pe;
;             psum += pe;
;           }
;           uint4 ov;
;           ov.x = pack2(pv[0], pv[1]); ov.y = pack2(pv[2], pv[3]);
;           ov.z = pack2(pv[4], pv[5]); ov.w = pack2(pv[6], pv[7]);
;           *reinterpret_cast<uint4*>(prow + s8 * 16) = ov;
;         }
;         psum += __shfl_xor(psum, 1);
;         l_run = l_run * alpha + psum;
;         m_run = m_new;
;         if (half == 0) alpha_s[row] = alpha;
	v_sub_f32_e32 v179, v179, v82
	v_sub_f32_e32 v180, v180, v82
	v_sub_f32_e32 v181, v181, v82
	v_exp_f32_e32 v179, v179
	v_exp_f32_e32 v180, v180
	v_exp_f32_e32 v181, v181
	v_add_u32_e32 v196, -15, v112
	v_add_u32_e32 v197, -16, v112
	v_add_u32_e32 v198, 0xffffffef, v112
	v_cmp_gt_u32_e32 vcc, s91, v196
	v_cmp_gt_u32_e64 s[92:93], s91, v197
	v_cmp_gt_u32_e64 s[94:95], s91, v198
	v_cndmask_b32_e32 v179, 0, v179, vcc
	v_cndmask_b32_e64 v180, 0, v180, s[92:93]
	v_cndmask_b32_e64 v181, 0, v181, s[94:95]
	v_add_f32_e32 v103, v103, v179
	v_add_f32_e32 v103, v103, v180
	v_add_f32_e32 v103, v103, v181
	s_waitcnt lgkmcnt(2)
	v_sub_f32_e32 v182, v182, v82
	v_sub_f32_e32 v183, v183, v82
	v_sub_f32_e32 v184, v184, v82
	v_exp_f32_e32 v182, v182
	v_exp_f32_e32 v183, v183
	v_exp_f32_e32 v184, v184
	v_add_u32_e32 v196, 0xffffffee, v112
	v_add_u32_e32 v197, 0xffffffed, v112
	v_add_u32_e32 v198, 0xffffffec, v112
	v_cmp_gt_u32_e32 vcc, s91, v196
	v_cmp_gt_u32_e64 s[92:93], s91, v197
	v_cmp_gt_u32_e64 s[94:95], s91, v198
	v_cndmask_b32_e32 v182, 0, v182, vcc
	v_cndmask_b32_e64 v183, 0, v183, s[92:93]
	v_cndmask_b32_e64 v184, 0, v184, s[94:95]
	v_add_f32_e32 v103, v103, v182
	v_add_f32_e32 v103, v103, v183
	v_add_f32_e32 v103, v103, v184
	v_sub_f32_e32 v185, v185, v82
	v_sub_f32_e32 v186, v186, v82
	v_sub_f32_e32 v187, v187, v82
	v_exp_f32_e32 v185, v185
	v_exp_f32_e32 v186, v186
	v_exp_f32_e32 v187, v187
	v_add_u32_e32 v196, 0xffffffeb, v112
	v_add_u32_e32 v197, 0xffffffea, v112
	v_add_u32_e32 v198, 0xffffffe9, v112
	v_cmp_gt_u32_e32 vcc, s91, v196
	v_cmp_gt_u32_e64 s[92:93], s91, v197
	v_cmp_gt_u32_e64 s[94:95], s91, v198
	v_cndmask_b32_e32 v185, 0, v185, vcc
	v_cndmask_b32_e64 v186, 0, v186, s[92:93]
	v_cndmask_b32_e64 v187, 0, v187, s[94:95]
	v_add_f32_e32 v103, v103, v185
	v_add_f32_e32 v103, v103, v186
	v_add_f32_e32 v103, v103, v187
	s_waitcnt lgkmcnt(1)
	v_sub_f32_e32 v188, v188, v82
	v_sub_f32_e32 v189, v189, v82
	v_sub_f32_e32 v190, v190, v82
	v_exp_f32_e32 v188, v188
	v_exp_f32_e32 v189, v189
	v_exp_f32_e32 v190, v190
	v_add_u32_e32 v196, 0xffffffe8, v112
	v_add_u32_e32 v197, 0xffffffe7, v112
	v_add_u32_e32 v198, 0xffffffe6, v112
	v_cmp_gt_u32_e32 vcc, s91, v196
	v_cmp_gt_u32_e64 s[92:93], s91, v197
	v_cmp_gt_u32_e64 s[94:95], s91, v198
	v_cndmask_b32_e32 v188, 0, v188, vcc
	v_cndmask_b32_e64 v189, 0, v189, s[92:93]
	v_cndmask_b32_e64 v190, 0, v190, s[94:95]
	v_add_f32_e32 v103, v103, v188
	v_add_f32_e32 v103, v103, v189
	v_add_f32_e32 v103, v103, v190
	s_waitcnt lgkmcnt(0)
	v_sub_f32_e32 v191, v191, v82
	v_sub_f32_e32 v192, v192, v82
	v_sub_f32_e32 v193, v193, v82
	v_exp_f32_e32 v191, v191
	v_exp_f32_e32 v192, v192
	v_exp_f32_e32 v193, v193
	v_add_u32_e32 v196, 0xffffffe5, v112
	v_add_u32_e32 v197, 0xffffffe4, v112
	v_add_u32_e32 v198, 0xffffffe3, v112
	v_cmp_gt_u32_e32 vcc, s91, v196
	v_cmp_gt_u32_e64 s[92:93], s91, v197
	v_cmp_gt_u32_e64 s[94:95], s91, v198
	v_cndmask_b32_e32 v191, 0, v191, vcc
	v_cndmask_b32_e64 v192, 0, v192, s[92:93]
	v_cndmask_b32_e64 v193, 0, v193, s[94:95]
	v_add_f32_e32 v103, v103, v191
	v_add_f32_e32 v103, v103, v192
	v_add_f32_e32 v103, v103, v193
	v_sub_f32_e32 v194, v194, v82
	v_sub_f32_e32 v195, v195, v82
	v_exp_f32_e32 v194, v194
	v_exp_f32_e32 v195, v195
	v_add_u32_e32 v196, 0xffffffe2, v112
	v_add_u32_e32 v197, 0xffffffe1, v112
	v_cmp_gt_u32_e32 vcc, s91, v196
	v_cmp_gt_u32_e64 s[92:93], s91, v197
	s_nop 0
	v_cndmask_b32_e32 v194, 0, v194, vcc
	v_cndmask_b32_e64 v195, 0, v195, s[92:93]
	v_add_f32_e32 v103, v103, v194
	v_add_f32_e32 v103, v103, v195
	v_cvt_pk_bf16_f32 v104, v164, v165
	v_cvt_pk_bf16_f32 v105, v166, v167
	v_cvt_pk_bf16_f32 v106, v168, v169
	v_cvt_pk_bf16_f32 v107, v170, v171
	ds_write_b128 v101, v[104:107]
	s_nop 0
	v_cvt_pk_bf16_f32 v104, v172, v173
	v_cvt_pk_bf16_f32 v105, v174, v175
	v_cvt_pk_bf16_f32 v106, v176, v177
	v_cvt_pk_bf16_f32 v107, v178, v179
	ds_write_b128 v101, v[104:107] offset:16
	s_nop 0
	v_cvt_pk_bf16_f32 v104, v180, v181
	v_cvt_pk_bf16_f32 v105, v182, v183
	v_cvt_pk_bf16_f32 v106, v184, v185
	v_cvt_pk_bf16_f32 v107, v186, v187
	ds_write_b128 v101, v[104:107] offset:32
	s_nop 0
	v_cvt_pk_bf16_f32 v104, v188, v189
	v_cvt_pk_bf16_f32 v105, v190, v191
	v_cvt_pk_bf16_f32 v106, v192, v193
	v_cvt_pk_bf16_f32 v107, v194, v195
	ds_write_b128 v101, v[104:107] offset:48
	v_sub_f32_e32 v101, v87, v82
	ds_bpermute_b32 v87, v83, v103
	v_exp_f32_e32 v83, v101
	s_and_saveexec_b64 s[6:7], s[4:5]
	ds_write_b32 v97, v83 offset:8192
	s_or_b64 exec, exec, s[6:7]
	s_waitcnt lgkmcnt(0)
	v_add_f32_e32 v101, v103, v87
	v_fmac_f32_e32 v101, v88, v83
	v_mov_b32_e32 v87, v82
	v_mov_b32_e32 v88, v101

; template <int DH, int MODE>
; __device__ void attn_item(const Params& p, int layer, int b, int blk, int head, char* smem) {
;     ...
;     __syncthreads();
;     V_SCATTER_(vr0, 0);
;     V_SCATTER_(vr1, 1);
;     if (KCH > 2) {
;       V_SCATTER_(vr2, 2);
;       V_SCATTER_(vr3, 3);
;     }
;     KV_LOAD_(it + 1);
;     if (!wskip) {
;       float4* s4 = reinterpret_cast<float4*>(Sf + row * SSTR + half * 32);
;       char* prow = Pb + half * 8192 + row * 64;
;       if (MODE == 0) {
;         const int kjb = kj0 + half * 32;
;         float tmax = -1e30f;
; #pragma unroll
;         for (int c = 0; c < 8; ++c) {
;           float4 v = s4[c];
;           float e[4] = {v.x, v.y, v.z, v.w};
; #pragma unroll
;           for (int k = 0; k < 4; ++k) {
;             int kj = kjb + c * 4 + k;
;             bool valid = (kj > row) && (kj <= row + 128);
;             tmax = valid ? fmaxf(tmax, e[k]) : tmax;
;           }
;         }
.LBB0_487:
	s_or_b64 exec, exec, s[14:15]
	s_add_i32 s89, s89, 1
	s_min_i32 s14, s89, s87
	s_add_i32 s14, s14, s86
	s_lshl_b32 s14, s14, 6
	s_add_i32 s14, s14, s88
	s_ashr_i32 s15, s14, 31
	s_add_u32 s14, s14, s84
	s_addc_u32 s15, s15, 0
	s_waitcnt lgkmcnt(0)
	s_barrier
	ds_write_b16 v96, v48
	ds_write_b16_d16_hi v96, v48 offset:64
	ds_write_b16 v96, v49 offset:128
	ds_write_b16_d16_hi v96, v49 offset:192
	ds_write_b16 v96, v50 offset:256
	ds_write_b16_d16_hi v96, v50 offset:320
	ds_write_b16 v96, v51 offset:384
	ds_write_b16_d16_hi v96, v51 offset:448
	s_waitcnt vmcnt(0)
	ds_write_b16 v96, v52 offset:2048
	ds_write_b16_d16_hi v96, v52 offset:2112
	ds_write_b16 v96, v53 offset:2176
	ds_write_b16_d16_hi v96, v53 offset:2240
	ds_write_b16 v96, v54 offset:2304
	ds_write_b16_d16_hi v96, v54 offset:2368
	ds_write_b16 v96, v55 offset:2432
	ds_write_b16_d16_hi v96, v55 offset:2496
	v_lshl_add_u64 v[48:49], s[14:15], 0, v[66:67]
	v_mad_u64_u32 v[52:53], s[20:21], v48, s63, v[76:77]
	v_or_b32_e32 v48, s14, v72
	v_mad_i32_i24 v53, v49, s63, v53
	v_mad_u64_u32 v[54:55], s[20:21], v48, s63, v[78:79]
	v_add_co_u32_e32 v48, vcc, 0x4c000, v52
	v_mad_i32_i24 v55, s15, v160, v55
	s_nop 0
	v_addc_co_u32_e32 v49, vcc, 0, v53, vcc
	global_load_dwordx4 v[60:63], v[48:49], off
	s_nop 0
	global_load_dwordx4 v[48:51], v[54:55], off
	global_load_dwordx4 v[56:59], v[52:53], off
	s_nop 0
	global_load_dwordx4 v[52:55], v[54:55], off offset:64
	s_and_saveexec_b64 s[54:55], s[52:53]
	s_cbranch_execz .LBB0_509
	v_or_b32_e32 v101, s16, v89
	s_movk_i32 s91, 0x80
	ds_read_b128 v[164:167], v90 offset:16384
	ds_read_b128 v[168:171], v90 offset:16400
	ds_read_b128 v[172:175], v90 offset:16416
	ds_read_b128 v[176:179], v90 offset:16432
	ds_read_b128 v[180:183], v90 offset:16448
	ds_read_b128 v[184:187], v90 offset:16464
	ds_read_b128 v[188:191], v90 offset:16480
	ds_read_b128 v[192:195], v90 offset:16496
	v_sub_u32_e32 v102, v80, v101
	v_mov_b32_e32 v83, 0xf149f2ca
	v_mov_b32_e32 v196, v102
	v_add_u32_e32 v197, -1, v102
	v_add_u32_e32 v198, -2, v102
	v_cmp_gt_u32_e32 vcc, s91, v196
	v_cmp_gt_u32_e64 s[92:93], s91, v197
	v_cmp_gt_u32_e64 s[94:95], s91, v198
	s_waitcnt lgkmcnt(7)
	v_cndmask_b32_e32 v164, v83, v164, vcc
	v_cndmask_b32_e64 v165, v83, v165, s[92:93]
	v_cndmask_b32_e64 v166, v83, v166, s[94:95]
	v_add_u32_e32 v196, -3, v102
	v_add_u32_e32 v197, -4, v102
	v_add_u32_e32 v198, -5, v102
	v_cmp_gt_u32_e32 vcc, s91, v196
	v_cmp_gt_u32_e64 s[92:93], s91, v197
	v_cmp_gt_u32_e64 s[94:95], s91, v198
	s_waitcnt lgkmcnt(6)
	v_cndmask_b32_e32 v167, v83, v167, vcc
	v_cndmask_b32_e64 v168, v83, v168, s[92:93]
	v_cndmask_b32_e64 v169, v83, v169, s[94:95]
	v_add_u32_e32 v196, -6, v102
	v_add_u32_e32 v197, -7, v102
	v_add_u32_e32 v198, -8, v102
	v_cmp_gt_u32_e32 vcc, s91, v196
	v_cmp_gt_u32_e64 s[92:93], s91, v197
	v_cmp_gt_u32_e64 s[94:95], s91, v198
	s_waitcnt lgkmcnt(5)
	v_cndmask_b32_e32 v170, v83, v170, vcc
	v_cndmask_b32_e64 v171, v83, v171, s[92:93]
	v_cndmask_b32_e64 v172, v83, v172, s[94:95]
	v_add_u32_e32 v196, -9, v102
	v_add_u32_e32 v197, -10, v102
	v_add_u32_e32 v198, -11, v102
	v_cmp_gt_u32_e32 vcc, s91, v196
	v_cmp_gt_u32_e64 s[92:93], s91, v197
	v_cmp_gt_u32_e64 s[94:95], s91, v198
	v_cndmask_b32_e32 v173, v83, v173, vcc
	v_cndmask_b32_e64 v174, v83, v174, s[92:93]
	v_cndmask_b32_e64 v175, v83, v175, s[94:95]
	v_add_u32_e32 v196, -12, v102
	v_add_u32_e32 v197, -13, v102
	v_add_u32_e32 v198, -14, v102
	v_cmp_gt_u32_e32 vcc, s91, v196
	v_cmp_gt_u32_e64 s[92:93], s91, v197
	v_cmp_gt_u32_e64 s[94:95], s91, v198
	s_waitcnt lgkmcnt(4)
	v_cndmask_b32_e32 v176, v83, v176, vcc
	v_cndmask_b32_e64 v177, v83, v177, s[92:93]
	v_cndmask_b32_e64 v178, v83, v178, s[94:95]
	v_add_u32_e32 v196, -15, v102
	v_add_u32_e32 v197, -16, v102
	v_add_u32_e32 v198, 0xffffffef, v102
	v_cmp_gt_u32_e32 vcc, s91, v196
	v_cmp_gt_u32_e64 s[92:93], s91, v197
	v_cmp_gt_u32_e64 s[94:95], s91, v198
	s_waitcnt lgkmcnt(3)
	v_cndmask_b32_e32 v179, v83, v179, vcc
	v_cndmask_b32_e64 v180, v83, v180, s[92:93]
	v_cndmask_b32_e64 v181, v83, v181, s[94:95]
	v_add_u32_e32 v196, 0xffffffee, v102
	v_add_u32_e32 v197, 0xffffffed, v102
	v_add_u32_e32 v198, 0xffffffec, v102
	v_cmp_gt_u32_e32 vcc, s91, v196
	v_cmp_gt_u32_e64 s[92:93], s91, v197
	v_cmp_gt_u32_e64 s[94:95], s91, v198
	s_waitcnt lgkmcnt(2)
	v_cndmask_b32_e32 v182, v83, v182, vcc
	v_cndmask_b32_e64 v183, v83, v183, s[92:93]
	v_cndmask_b32_e64 v184, v83, v184, s[94:95]
	v_add_u32_e32 v196, 0xffffffeb, v102
	v_add_u32_e32 v197, 0xffffffea, v102
	v_add_u32_e32 v198, 0xffffffe9, v102
	v_cmp_gt_u32_e32 vcc, s91, v196
	v_cmp_gt_u32_e64 s[92:93], s91, v197
	v_cmp_gt_u32_e64 s[94:95], s91, v198
	v_cndmask_b32_e32 v185, v83, v185, vcc
	v_cndmask_b32_e64 v186, v83, v186, s[92:93]
	v_cndmask_b32_e64 v187, v83, v187, s[94:95]
	v_add_u32_e32 v196, 0xffffffe8, v102
	v_add_u32_e32 v197, 0xffffffe7, v102
	v_add_u32_e32 v198, 0xffffffe6, v102
	v_cmp_gt_u32_e32 vcc, s91, v196
	v_cmp_gt_u32_e64 s[92:93], s91, v197
	v_cmp_gt_u32_e64 s[94:95], s91, v198
	s_waitcnt lgkmcnt(1)
	v_cndmask_b32_e32 v188, v83, v188, vcc
	v_cndmask_b32_e64 v189, v83, v189, s[92:93]
	v_cndmask_b32_e64 v190, v83, v190, s[94:95]
	v_add_u32_e32 v196, 0xffffffe5, v102
	v_add_u32_e32 v197, 0xffffffe4, v102
	v_add_u32_e32 v198, 0xffffffe3, v102
	v_cmp_gt_u32_e32 vcc, s91, v196
	v_cmp_gt_u32_e64 s[92:93], s91, v197
	v_cmp_gt_u32_e64 s[94:95], s91, v198
	s_waitcnt lgkmcnt(0)
; template <int DH, int MODE>
; __device__ void attn_item(const Params& p, int layer, int b, int blk, int head, char* smem) {
;     ...
; #pragma unroll
;         for (int c = 0; c < 8; ++c) {
;           float4 v = s4[c];
;           float e[4] = {v.x, v.y, v.z, v.w};
; #pragma unroll
;           for (int k = 0; k < 4; ++k) {
;             int kj = kjb + c * 4 + k;
;             bool valid = (kj > row) && (kj <= row + 128);
;             tmax = valid ? fmaxf(tmax, e[k]) : tmax;
;           }
;         }
;         tmax = fmaxf(tmax, __shfl_xor(tmax, 1));
;         float m_new = fmaxf(m_run, tmax);
;         float alpha = __builtin_amdgcn_exp2f(m_run - m_new);
;         float psum = 0.f;
; #pragma unroll 2
;         for (int s8 = 0; s8 < 4; ++s8) {
;           float4 va = s4[2 * s8], vb = s4[2 * s8 + 1];
;           float e[8] = {va.x, va.y, va.z, va.w, vb.x, vb.y, vb.z, vb.w};
;           float pv[8];
; #pragma unroll
;           for (int k = 0; k < 8; ++k) {
;             int kj = kjb + s8 * 8 + k;
;             bool valid = (kj > row) && (kj <= row + 128);
;             float pe = valid ? __builtin_amdgcn_exp2f(e[k] - m_new) : 0.f;
;             pv[k] = pe;
;             psum += pe;
;           }
	v_cndmask_b32_e32 v191, v83, v191, vcc
	v_cndmask_b32_e64 v192, v83, v192, s[92:93]
	v_cndmask_b32_e64 v193, v83, v193, s[94:95]
	v_add_u32_e32 v196, 0xffffffe2, v102
	v_add_u32_e32 v197, 0xffffffe1, v102
	v_cmp_gt_u32_e32 vcc, s91, v196
	v_cmp_gt_u32_e64 s[92:93], s91, v197
	s_nop 0
	v_cndmask_b32_e32 v194, v83, v194, vcc
	v_cndmask_b32_e64 v195, v83, v195, s[92:93]
	v_max3_f32 v164, v164, v165, v166
	v_max3_f32 v167, v167, v168, v169
	v_max3_f32 v170, v170, v171, v172
	v_max3_f32 v173, v173, v174, v175
	v_max3_f32 v176, v176, v177, v178
	v_max3_f32 v179, v179, v180, v181
	v_max3_f32 v182, v182, v183, v184
	v_max3_f32 v185, v185, v186, v187
	v_max3_f32 v188, v188, v189, v190
	v_max3_f32 v191, v191, v192, v193
	v_max_f32_e32 v194, v194, v195
	v_max3_f32 v164, v164, v167, v170
	v_max3_f32 v173, v173, v176, v179
	v_max3_f32 v182, v182, v185, v188
	v_max_f32_e32 v191, v191, v194
	v_max3_f32 v164, v164, v173, v182
	v_max_f32_e32 v164, v164, v191
	v_mov_b32_e32 v82, v164
	v_cmp_lt_i32_e32 vcc, v157, v158
	s_mov_b32 s90, 0
	v_mov_b32_e32 v103, 0
	v_cndmask_b32_e32 v83, v156, v157, vcc
	v_lshlrev_b32_e32 v83, 2, v83
	ds_bpermute_b32 v101, v83, v82
	v_mov_b32_e32 v102, v91
	s_waitcnt lgkmcnt(0)
	v_max3_f32 v82, v87, v82, v101
	v_mov_b32_e32 v101, v93
	ds_read_b128 v[164:167], v102
	ds_read_b128 v[168:171], v102 offset:16
	ds_read_b128 v[172:175], v102 offset:32
	ds_read_b128 v[176:179], v102 offset:48
	ds_read_b128 v[180:183], v102 offset:64
	ds_read_b128 v[184:187], v102 offset:80
	ds_read_b128 v[188:191], v102 offset:96
	ds_read_b128 v[192:195], v102 offset:112
	s_movk_i32 s91, 0x80
	v_sub_u32_e32 v112, v80, v92
	s_waitcnt lgkmcnt(7)
	v_sub_f32_e32 v164, v164, v82
	v_sub_f32_e32 v165, v165, v82
	v_sub_f32_e32 v166, v166, v82
	v_exp_f32_e32 v164, v164
	v_exp_f32_e32 v165, v165
	v_exp_f32_e32 v166, v166
	v_mov_b32_e32 v196, v112
	v_add_u32_e32 v197, -1, v112
	v_add_u32_e32 v198, -2, v112
	v_cmp_gt_u32_e32 vcc, s91, v196
	v_cmp_gt_u32_e64 s[92:93], s91, v197
	v_cmp_gt_u32_e64 s[94:95], s91, v198
	v_cndmask_b32_e32 v164, 0, v164, vcc
	v_cndmask_b32_e64 v165, 0, v165, s[92:93]
	v_cndmask_b32_e64 v166, 0, v166, s[94:95]
	v_add_f32_e32 v103, v103, v164
	v_add_f32_e32 v103, v103, v165
	v_add_f32_e32 v103, v103, v166
	s_waitcnt lgkmcnt(6)
	v_sub_f32_e32 v167, v167, v82
	v_sub_f32_e32 v168, v168, v82
	v_sub_f32_e32 v169, v169, v82
	v_exp_f32_e32 v167, v167
	v_exp_f32_e32 v168, v168
	v_exp_f32_e32 v169, v169
	v_add_u32_e32 v196, -3, v112
	v_add_u32_e32 v197, -4, v112
	v_add_u32_e32 v198, -5, v112
	v_cmp_gt_u32_e32 vcc, s91, v196
	v_cmp_gt_u32_e64 s[92:93], s91, v197
	v_cmp_gt_u32_e64 s[94:95], s91, v198
	v_cndmask_b32_e32 v167, 0, v167, vcc
	v_cndmask_b32_e64 v168, 0, v168, s[92:93]
	v_cndmask_b32_e64 v169, 0, v169, s[94:95]
	v_add_f32_e32 v103, v103, v167
	v_add_f32_e32 v103, v103, v168
	v_add_f32_e32 v103, v103, v169
	s_waitcnt lgkmcnt(5)
	v_sub_f32_e32 v170, v170, v82
	v_sub_f32_e32 v171, v171, v82
	v_sub_f32_e32 v172, v172, v82
	v_exp_f32_e32 v170, v170
	v_exp_f32_e32 v171, v171
	v_exp_f32_e32 v172, v172
	v_add_u32_e32 v196, -6, v112
	v_add_u32_e32 v197, -7, v112
	v_add_u32_e32 v198, -8, v112
	v_cmp_gt_u32_e32 vcc, s91, v196
	v_cmp_gt_u32_e64 s[92:93], s91, v197
	v_cmp_gt_u32_e64 s[94:95], s91, v198
	v_cndmask_b32_e32 v170, 0, v170, vcc
	v_cndmask_b32_e64 v171, 0, v171, s[92:93]
	v_cndmask_b32_e64 v172, 0, v172, s[94:95]
	v_add_f32_e32 v103, v103, v170
	v_add_f32_e32 v103, v103, v171
	v_add_f32_e32 v103, v103, v172
	v_sub_f32_e32 v173, v173, v82
	v_sub_f32_e32 v174, v174, v82
	v_sub_f32_e32 v175, v175, v82
	v_exp_f32_e32 v173, v173
	v_exp_f32_e32 v174, v174
	v_exp_f32_e32 v175, v175
	v_add_u32_e32 v196, -9, v112
	v_add_u32_e32 v197, -10, v112
	v_add_u32_e32 v198, -11, v112
	v_cmp_gt_u32_e32 vcc, s91, v196
	v_cmp_gt_u32_e64 s[92:93], s91, v197
	v_cmp_gt_u32_e64 s[94:95], s91, v198
	v_cndmask_b32_e32 v173, 0, v173, vcc
	v_cndmask_b32_e64 v174, 0, v174, s[92:93]
	v_cndmask_b32_e64 v175, 0, v175, s[94:95]
	v_add_f32_e32 v103, v103, v173
	v_add_f32_e32 v103, v103, v174
	v_add_f32_e32 v103, v103, v175
	s_waitcnt lgkmcnt(4)
	v_sub_f32_e32 v176, v176, v82
	v_sub_f32_e32 v177, v177, v82
	v_sub_f32_e32 v178, v178, v82
	v_exp_f32_e32 v176, v176
	v_exp_f32_e32 v177, v177
	v_exp_f32_e32 v178, v178
	v_add_u32_e32 v196, -12, v112
	v_add_u32_e32 v197, -13, v112
	v_add_u32_e32 v198, -14, v112
	v_cmp_gt_u32_e32 vcc, s91, v196
	v_cmp_gt_u32_e64 s[92:93], s91, v197
	v_cmp_gt_u32_e64 s[94:95], s91, v198
	v_cndmask_b32_e32 v176, 0, v176, vcc
	v_cndmask_b32_e64 v177, 0, v177, s[92:93]
	v_cndmask_b32_e64 v178, 0, v178, s[94:95]
	v_add_f32_e32 v103, v103, v176
	v_add_f32_e32 v103, v103, v177
	v_add_f32_e32 v103, v103, v178
	s_waitcnt lgkmcnt(3)
; __device__ __forceinline__ unsigned pack2(float a, float b) { return (unsigned)f2bf(a) | ((unsigned)f2bf(b) << 16); }
; template <int DH, int MODE>
; __device__ void attn_item(const Params& p, int layer, int b, int blk, int head, char* smem) {
;     ...
; #pragma unroll 2
;         for (int s8 = 0; s8 < 4; ++s8) {
;           float4 va = s4[2 * s8], vb = s4[2 * s8 + 1];
;           float e[8] = {va.x, va.y, va.z, va.w, vb.x, vb.y, vb.z, vb.w};
;           float pv[8];
; #pragma unroll
;           for (int k = 0; k < 8; ++k) {
;             int kj = kjb + s8 * 8 + k;
;             bool valid = (kj > row) && (kj <= row + 128);
;             float pe = valid ? __builtin_amdgcn_exp2f(e[k] - m_new) : 0.f;
;             pv[k] = pe;
;             psum += pe;
;           }
;           uint4 ov;
;           ov.x = pack2(pv[0], pv[1]); ov.y = pack2(pv[2], pv[3]);
;           ov.z = pack2(pv[4], pv[5]); ov.w = pack2(pv[6], pv[7]);
;           *reinterpret_cast<uint4*>(prow + s8 * 16) = ov;
;         }
;         psum += __shfl_xor(psum, 1);
;         l_run = l_run * alpha + psum;
;         m_run = m_new;
;         if (half == 0) alpha_s[row] = alpha;
	v_sub_f32_e32 v179, v179, v82
	v_sub_f32_e32 v180, v180, v82
	v_sub_f32_e32 v181, v181, v82
	v_exp_f32_e32 v179, v179
	v_exp_f32_e32 v180, v180
	v_exp_f32_e32 v181, v181
	v_add_u32_e32 v196, -15, v112
	v_add_u32_e32 v197, -16, v112
	v_add_u32_e32 v198, 0xffffffef, v112
	v_cmp_gt_u32_e32 vcc, s91, v196
	v_cmp_gt_u32_e64 s[92:93], s91, v197
	v_cmp_gt_u32_e64 s[94:95], s91, v198
	v_cndmask_b32_e32 v179, 0, v179, vcc
	v_cndmask_b32_e64 v180, 0, v180, s[92:93]
	v_cndmask_b32_e64 v181, 0, v181, s[94:95]
	v_add_f32_e32 v103, v103, v179
	v_add_f32_e32 v103, v103, v180
	v_add_f32_e32 v103, v103, v181
	s_waitcnt lgkmcnt(2)
	v_sub_f32_e32 v182, v182, v82
	v_sub_f32_e32 v183, v183, v82
	v_sub_f32_e32 v184, v184, v82
	v_exp_f32_e32 v182, v182
	v_exp_f32_e32 v183, v183
	v_exp_f32_e32 v184, v184
	v_add_u32_e32 v196, 0xffffffee, v112
	v_add_u32_e32 v197, 0xffffffed, v112
	v_add_u32_e32 v198, 0xffffffec, v112
	v_cmp_gt_u32_e32 vcc, s91, v196
	v_cmp_gt_u32_e64 s[92:93], s91, v197
	v_cmp_gt_u32_e64 s[94:95], s91, v198
	v_cndmask_b32_e32 v182, 0, v182, vcc
	v_cndmask_b32_e64 v183, 0, v183, s[92:93]
	v_cndmask_b32_e64 v184, 0, v184, s[94:95]
	v_add_f32_e32 v103, v103, v182
	v_add_f32_e32 v103, v103, v183
	v_add_f32_e32 v103, v103, v184
	v_sub_f32_e32 v185, v185, v82
	v_sub_f32_e32 v186, v186, v82
	v_sub_f32_e32 v187, v187, v82
	v_exp_f32_e32 v185, v185
	v_exp_f32_e32 v186, v186
	v_exp_f32_e32 v187, v187
	v_add_u32_e32 v196, 0xffffffeb, v112
	v_add_u32_e32 v197, 0xffffffea, v112
	v_add_u32_e32 v198, 0xffffffe9, v112
	v_cmp_gt_u32_e32 vcc, s91, v196
	v_cmp_gt_u32_e64 s[92:93], s91, v197
	v_cmp_gt_u32_e64 s[94:95], s91, v198
	v_cndmask_b32_e32 v185, 0, v185, vcc
	v_cndmask_b32_e64 v186, 0, v186, s[92:93]
	v_cndmask_b32_e64 v187, 0, v187, s[94:95]
	v_add_f32_e32 v103, v103, v185
	v_add_f32_e32 v103, v103, v186
	v_add_f32_e32 v103, v103, v187
	s_waitcnt lgkmcnt(1)
	v_sub_f32_e32 v188, v188, v82
	v_sub_f32_e32 v189, v189, v82
	v_sub_f32_e32 v190, v190, v82
	v_exp_f32_e32 v188, v188
	v_exp_f32_e32 v189, v189
	v_exp_f32_e32 v190, v190
	v_add_u32_e32 v196, 0xffffffe8, v112
	v_add_u32_e32 v197, 0xffffffe7, v112
	v_add_u32_e32 v198, 0xffffffe6, v112
	v_cmp_gt_u32_e32 vcc, s91, v196
	v_cmp_gt_u32_e64 s[92:93], s91, v197
	v_cmp_gt_u32_e64 s[94:95], s91, v198
	v_cndmask_b32_e32 v188, 0, v188, vcc
	v_cndmask_b32_e64 v189, 0, v189, s[92:93]
	v_cndmask_b32_e64 v190, 0, v190, s[94:95]
	v_add_f32_e32 v103, v103, v188
	v_add_f32_e32 v103, v103, v189
	v_add_f32_e32 v103, v103, v190
	s_waitcnt lgkmcnt(0)
	v_sub_f32_e32 v191, v191, v82
	v_sub_f32_e32 v192, v192, v82
	v_sub_f32_e32 v193, v193, v82
	v_exp_f32_e32 v191, v191
	v_exp_f32_e32 v192, v192
	v_exp_f32_e32 v193, v193
	v_add_u32_e32 v196, 0xffffffe5, v112
	v_add_u32_e32 v197, 0xffffffe4, v112
	v_add_u32_e32 v198, 0xffffffe3, v112
	v_cmp_gt_u32_e32 vcc, s91, v196
	v_cmp_gt_u32_e64 s[92:93], s91, v197
	v_cmp_gt_u32_e64 s[94:95], s91, v198
	v_cndmask_b32_e32 v191, 0, v191, vcc
	v_cndmask_b32_e64 v192, 0, v192, s[92:93]
	v_cndmask_b32_e64 v193, 0, v193, s[94:95]
	v_add_f32_e32 v103, v103, v191
	v_add_f32_e32 v103, v103, v192
	v_add_f32_e32 v103, v103, v193
	v_sub_f32_e32 v194, v194, v82
	v_sub_f32_e32 v195, v195, v82
	v_exp_f32_e32 v194, v194
	v_exp_f32_e32 v195, v195
	v_add_u32_e32 v196, 0xffffffe2, v112
	v_add_u32_e32 v197, 0xffffffe1, v112
	v_cmp_gt_u32_e32 vcc, s91, v196
	v_cmp_gt_u32_e64 s[92:93], s91, v197
	s_nop 0
	v_cndmask_b32_e32 v194, 0, v194, vcc
	v_cndmask_b32_e64 v195, 0, v195, s[92:93]
	v_add_f32_e32 v103, v103, v194
	v_add_f32_e32 v103, v103, v195
	v_cvt_pk_bf16_f32 v104, v164, v165
	v_cvt_pk_bf16_f32 v105, v166, v167
	v_cvt_pk_bf16_f32 v106, v168, v169
	v_cvt_pk_bf16_f32 v107, v170, v171
	ds_write_b128 v101, v[104:107]
	s_nop 0
	v_cvt_pk_bf16_f32 v104, v172, v173
	v_cvt_pk_bf16_f32 v105, v174, v175
	v_cvt_pk_bf16_f32 v106, v176, v177
	v_cvt_pk_bf16_f32 v107, v178, v179
	ds_write_b128 v101, v[104:107] offset:16
	s_nop 0
	v_cvt_pk_bf16_f32 v104, v180, v181
	v_cvt_pk_bf16_f32 v105, v182, v183
	v_cvt_pk_bf16_f32 v106, v184, v185
	v_cvt_pk_bf16_f32 v107, v186, v187
	ds_write_b128 v101, v[104:107] offset:32
	s_nop 0
	v_cvt_pk_bf16_f32 v104, v188, v189
	v_cvt_pk_bf16_f32 v105, v190, v191
	v_cvt_pk_bf16_f32 v106, v192, v193
	v_cvt_pk_bf16_f32 v107, v194, v195
	ds_write_b128 v101, v[104:107] offset:48
	v_sub_f32_e32 v101, v87, v82
	ds_bpermute_b32 v87, v83, v103
	v_exp_f32_e32 v83, v101
	s_and_saveexec_b64 s[14:15], s[12:13]
	ds_write_b32 v97, v83 offset:8192
	s_or_b64 exec, exec, s[14:15]
	s_waitcnt lgkmcnt(0)
	v_add_f32_e32 v101, v103, v87
	v_fmac_f32_e32 v101, v88, v83
	v_mov_b32_e32 v87, v82
	v_mov_b32_e32 v88, v101

; template <int DH, int MODE>
; __device__ void attn_item(const Params& p, int layer, int b, int blk, int head, char* smem) {
;     ...
;     __syncthreads();
;     V_SCATTER_(vr0, 0);
;     V_SCATTER_(vr1, 1);
;     if (KCH > 2) {
;       V_SCATTER_(vr2, 2);
;       V_SCATTER_(vr3, 3);
;     }
;     KV_LOAD_(it + 1);
;     if (!wskip) {
;       float4* s4 = reinterpret_cast<float4*>(Sf + row * SSTR + half * 32);
;       char* prow = Pb + half * 8192 + row * 64;
;       if (MODE == 0) {
;         const int kjb = kj0 + half * 32;
;         float tmax = -1e30f;
; #pragma unroll
;         for (int c = 0; c < 8; ++c) {
;           float4 v = s4[c];
;           float e[4] = {v.x, v.y, v.z, v.w};
; #pragma unroll
;           for (int k = 0; k < 4; ++k) {
;             int kj = kjb + c * 4 + k;
;             bool valid = (kj > row) && (kj <= row + 128);
;             tmax = valid ? fmaxf(tmax, e[k]) : tmax;
;           }
;         }
.LBB0_808:
	s_or_b64 exec, exec, s[14:15]
	s_add_i32 s89, s89, 1
	s_min_i32 s14, s89, s87
	s_add_i32 s14, s14, s86
	s_lshl_b32 s14, s14, 6
	s_add_i32 s14, s14, s88
	s_ashr_i32 s15, s14, 31
	s_add_u32 s14, s14, s84
	s_addc_u32 s15, s15, 0
	s_waitcnt lgkmcnt(0)
	s_barrier
	ds_write_b16 v96, v48
	ds_write_b16_d16_hi v96, v48 offset:64
	ds_write_b16 v96, v49 offset:128
	ds_write_b16_d16_hi v96, v49 offset:192
	ds_write_b16 v96, v50 offset:256
	ds_write_b16_d16_hi v96, v50 offset:320
	ds_write_b16 v96, v51 offset:384
	ds_write_b16_d16_hi v96, v51 offset:448
	s_waitcnt vmcnt(0)
	ds_write_b16 v96, v52 offset:2048
	ds_write_b16_d16_hi v96, v52 offset:2112
	ds_write_b16 v96, v53 offset:2176
	ds_write_b16_d16_hi v96, v53 offset:2240
	ds_write_b16 v96, v54 offset:2304
	ds_write_b16_d16_hi v96, v54 offset:2368
	ds_write_b16 v96, v55 offset:2432
	ds_write_b16_d16_hi v96, v55 offset:2496
	v_lshl_add_u64 v[48:49], s[14:15], 0, v[66:67]
	v_mad_u64_u32 v[52:53], s[20:21], v48, s45, v[76:77]
	v_or_b32_e32 v48, s14, v72
	v_mad_i32_i24 v53, v49, s45, v53
	v_mad_u64_u32 v[54:55], s[20:21], v48, s45, v[78:79]
	v_add_co_u32_e32 v48, vcc, 0x4c000, v52
	v_mad_i32_i24 v55, s15, v160, v55
	s_nop 0
	v_addc_co_u32_e32 v49, vcc, 0, v53, vcc
	global_load_dwordx4 v[60:63], v[48:49], off
	s_nop 0
	global_load_dwordx4 v[48:51], v[54:55], off
	global_load_dwordx4 v[56:59], v[52:53], off
	s_nop 0
	global_load_dwordx4 v[52:55], v[54:55], off offset:64
	s_and_saveexec_b64 s[52:53], s[50:51]
	s_cbranch_execz .LBB0_830
	v_or_b32_e32 v101, s16, v89
	s_movk_i32 s91, 0x80
	ds_read_b128 v[164:167], v90 offset:16384
	ds_read_b128 v[168:171], v90 offset:16400
	ds_read_b128 v[172:175], v90 offset:16416
	ds_read_b128 v[176:179], v90 offset:16432
	ds_read_b128 v[180:183], v90 offset:16448
	ds_read_b128 v[184:187], v90 offset:16464
	ds_read_b128 v[188:191], v90 offset:16480
	ds_read_b128 v[192:195], v90 offset:16496
	v_sub_u32_e32 v102, v80, v101
	v_mov_b32_e32 v83, 0xf149f2ca
	v_mov_b32_e32 v196, v102
	v_add_u32_e32 v197, -1, v102
	v_add_u32_e32 v198, -2, v102
	v_cmp_gt_u32_e32 vcc, s91, v196
	v_cmp_gt_u32_e64 s[92:93], s91, v197
	v_cmp_gt_u32_e64 s[94:95], s91, v198
	s_waitcnt lgkmcnt(7)
	v_cndmask_b32_e32 v164, v83, v164, vcc
	v_cndmask_b32_e64 v165, v83, v165, s[92:93]
	v_cndmask_b32_e64 v166, v83, v166, s[94:95]
	v_add_u32_e32 v196, -3, v102
	v_add_u32_e32 v197, -4, v102
	v_add_u32_e32 v198, -5, v102
	v_cmp_gt_u32_e32 vcc, s91, v196
	v_cmp_gt_u32_e64 s[92:93], s91, v197
	v_cmp_gt_u32_e64 s[94:95], s91, v198
	s_waitcnt lgkmcnt(6)
	v_cndmask_b32_e32 v167, v83, v167, vcc
	v_cndmask_b32_e64 v168, v83, v168, s[92:93]
	v_cndmask_b32_e64 v169, v83, v169, s[94:95]
	v_add_u32_e32 v196, -6, v102
	v_add_u32_e32 v197, -7, v102
	v_add_u32_e32 v198, -8, v102
	v_cmp_gt_u32_e32 vcc, s91, v196
	v_cmp_gt_u32_e64 s[92:93], s91, v197
	v_cmp_gt_u32_e64 s[94:95], s91, v198
	s_waitcnt lgkmcnt(5)
	v_cndmask_b32_e32 v170, v83, v170, vcc
	v_cndmask_b32_e64 v171, v83, v171, s[92:93]
	v_cndmask_b32_e64 v172, v83, v172, s[94:95]
	v_add_u32_e32 v196, -9, v102
	v_add_u32_e32 v197, -10, v102
	v_add_u32_e32 v198, -11, v102
	v_cmp_gt_u32_e32 vcc, s91, v196
	v_cmp_gt_u32_e64 s[92:93], s91, v197
	v_cmp_gt_u32_e64 s[94:95], s91, v198
	v_cndmask_b32_e32 v173, v83, v173, vcc
	v_cndmask_b32_e64 v174, v83, v174, s[92:93]
	v_cndmask_b32_e64 v175, v83, v175, s[94:95]
	v_add_u32_e32 v196, -12, v102
	v_add_u32_e32 v197, -13, v102
	v_add_u32_e32 v198, -14, v102
	v_cmp_gt_u32_e32 vcc, s91, v196
	v_cmp_gt_u32_e64 s[92:93], s91, v197
	v_cmp_gt_u32_e64 s[94:95], s91, v198
	s_waitcnt lgkmcnt(4)
	v_cndmask_b32_e32 v176, v83, v176, vcc
	v_cndmask_b32_e64 v177, v83, v177, s[92:93]
	v_cndmask_b32_e64 v178, v83, v178, s[94:95]
	v_add_u32_e32 v196, -15, v102
	v_add_u32_e32 v197, -16, v102
	v_add_u32_e32 v198, 0xffffffef, v102
	v_cmp_gt_u32_e32 vcc, s91, v196
	v_cmp_gt_u32_e64 s[92:93], s91, v197
	v_cmp_gt_u32_e64 s[94:95], s91, v198
	s_waitcnt lgkmcnt(3)
	v_cndmask_b32_e32 v179, v83, v179, vcc
	v_cndmask_b32_e64 v180, v83, v180, s[92:93]
	v_cndmask_b32_e64 v181, v83, v181, s[94:95]
	v_add_u32_e32 v196, 0xffffffee, v102
	v_add_u32_e32 v197, 0xffffffed, v102
	v_add_u32_e32 v198, 0xffffffec, v102
	v_cmp_gt_u32_e32 vcc, s91, v196
	v_cmp_gt_u32_e64 s[92:93], s91, v197
	v_cmp_gt_u32_e64 s[94:95], s91, v198
	s_waitcnt lgkmcnt(2)
	v_cndmask_b32_e32 v182, v83, v182, vcc
	v_cndmask_b32_e64 v183, v83, v183, s[92:93]
	v_cndmask_b32_e64 v184, v83, v184, s[94:95]
	v_add_u32_e32 v196, 0xffffffeb, v102
	v_add_u32_e32 v197, 0xffffffea, v102
	v_add_u32_e32 v198, 0xffffffe9, v102
	v_cmp_gt_u32_e32 vcc, s91, v196
	v_cmp_gt_u32_e64 s[92:93], s91, v197
	v_cmp_gt_u32_e64 s[94:95], s91, v198
	v_cndmask_b32_e32 v185, v83, v185, vcc
	v_cndmask_b32_e64 v186, v83, v186, s[92:93]
	v_cndmask_b32_e64 v187, v83, v187, s[94:95]
	v_add_u32_e32 v196, 0xffffffe8, v102
	v_add_u32_e32 v197, 0xffffffe7, v102
	v_add_u32_e32 v198, 0xffffffe6, v102
	v_cmp_gt_u32_e32 vcc, s91, v196
	v_cmp_gt_u32_e64 s[92:93], s91, v197
	v_cmp_gt_u32_e64 s[94:95], s91, v198
	s_waitcnt lgkmcnt(1)
	v_cndmask_b32_e32 v188, v83, v188, vcc
	v_cndmask_b32_e64 v189, v83, v189, s[92:93]
	v_cndmask_b32_e64 v190, v83, v190, s[94:95]
	v_add_u32_e32 v196, 0xffffffe5, v102
	v_add_u32_e32 v197, 0xffffffe4, v102
	v_add_u32_e32 v198, 0xffffffe3, v102
	v_cmp_gt_u32_e32 vcc, s91, v196
	v_cmp_gt_u32_e64 s[92:93], s91, v197
	v_cmp_gt_u32_e64 s[94:95], s91, v198
	s_waitcnt lgkmcnt(0)
; template <int DH, int MODE>
; __device__ void attn_item(const Params& p, int layer, int b, int blk, int head, char* smem) {
;     ...
; #pragma unroll
;         for (int c = 0; c < 8; ++c) {
;           float4 v = s4[c];
;           float e[4] = {v.x, v.y, v.z, v.w};
; #pragma unroll
;           for (int k = 0; k < 4; ++k) {
;             int kj = kjb + c * 4 + k;
;             bool valid = (kj > row) && (kj <= row + 128);
;             tmax = valid ? fmaxf(tmax, e[k]) : tmax;
;           }
;         }
;         tmax = fmaxf(tmax, __shfl_xor(tmax, 1));
;         float m_new = fmaxf(m_run, tmax);
;         float alpha = __builtin_amdgcn_exp2f(m_run - m_new);
;         float psum = 0.f;
; #pragma unroll 2
;         for (int s8 = 0; s8 < 4; ++s8) {
;           float4 va = s4[2 * s8], vb = s4[2 * s8 + 1];
;           float e[8] = {va.x, va.y, va.z, va.w, vb.x, vb.y, vb.z, vb.w};
;           float pv[8];
; #pragma unroll
;           for (int k = 0; k < 8; ++k) {
;             int kj = kjb + s8 * 8 + k;
;             bool valid = (kj > row) && (kj <= row + 128);
;             float pe = valid ? __builtin_amdgcn_exp2f(e[k] - m_new) : 0.f;
;             pv[k] = pe;
;             psum += pe;
;           }
	v_cndmask_b32_e32 v191, v83, v191, vcc
	v_cndmask_b32_e64 v192, v83, v192, s[92:93]
	v_cndmask_b32_e64 v193, v83, v193, s[94:95]
	v_add_u32_e32 v196, 0xffffffe2, v102
	v_add_u32_e32 v197, 0xffffffe1, v102
	v_cmp_gt_u32_e32 vcc, s91, v196
	v_cmp_gt_u32_e64 s[92:93], s91, v197
	s_nop 0
	v_cndmask_b32_e32 v194, v83, v194, vcc
	v_cndmask_b32_e64 v195, v83, v195, s[92:93]
	v_max3_f32 v164, v164, v165, v166
	v_max3_f32 v167, v167, v168, v169
	v_max3_f32 v170, v170, v171, v172
	v_max3_f32 v173, v173, v174, v175
	v_max3_f32 v176, v176, v177, v178
	v_max3_f32 v179, v179, v180, v181
	v_max3_f32 v182, v182, v183, v184
	v_max3_f32 v185, v185, v186, v187
	v_max3_f32 v188, v188, v189, v190
	v_max3_f32 v191, v191, v192, v193
	v_max_f32_e32 v194, v194, v195
	v_max3_f32 v164, v164, v167, v170
	v_max3_f32 v173, v173, v176, v179
	v_max3_f32 v182, v182, v185, v188
	v_max_f32_e32 v191, v191, v194
	v_max3_f32 v164, v164, v173, v182
	v_max_f32_e32 v164, v164, v191
	v_mov_b32_e32 v82, v164
	v_cmp_lt_i32_e32 vcc, v157, v158
	s_mov_b32 s90, 0
	v_mov_b32_e32 v103, 0
	v_cndmask_b32_e32 v83, v156, v157, vcc
	v_lshlrev_b32_e32 v83, 2, v83
	ds_bpermute_b32 v101, v83, v82
	v_mov_b32_e32 v102, v91
	s_waitcnt lgkmcnt(0)
	v_max3_f32 v82, v87, v82, v101
	v_mov_b32_e32 v101, v93
	ds_read_b128 v[164:167], v102
	ds_read_b128 v[168:171], v102 offset:16
	ds_read_b128 v[172:175], v102 offset:32
	ds_read_b128 v[176:179], v102 offset:48
	ds_read_b128 v[180:183], v102 offset:64
	ds_read_b128 v[184:187], v102 offset:80
	ds_read_b128 v[188:191], v102 offset:96
	ds_read_b128 v[192:195], v102 offset:112
	s_movk_i32 s91, 0x80
	v_sub_u32_e32 v112, v80, v92
	s_waitcnt lgkmcnt(7)
	v_sub_f32_e32 v164, v164, v82
	v_sub_f32_e32 v165, v165, v82
	v_sub_f32_e32 v166, v166, v82
	v_exp_f32_e32 v164, v164
	v_exp_f32_e32 v165, v165
	v_exp_f32_e32 v166, v166
	v_mov_b32_e32 v196, v112
	v_add_u32_e32 v197, -1, v112
	v_add_u32_e32 v198, -2, v112
	v_cmp_gt_u32_e32 vcc, s91, v196
	v_cmp_gt_u32_e64 s[92:93], s91, v197
	v_cmp_gt_u32_e64 s[94:95], s91, v198
	v_cndmask_b32_e32 v164, 0, v164, vcc
	v_cndmask_b32_e64 v165, 0, v165, s[92:93]
	v_cndmask_b32_e64 v166, 0, v166, s[94:95]
	v_add_f32_e32 v103, v103, v164
	v_add_f32_e32 v103, v103, v165
	v_add_f32_e32 v103, v103, v166
	s_waitcnt lgkmcnt(6)
	v_sub_f32_e32 v167, v167, v82
	v_sub_f32_e32 v168, v168, v82
	v_sub_f32_e32 v169, v169, v82
	v_exp_f32_e32 v167, v167
	v_exp_f32_e32 v168, v168
	v_exp_f32_e32 v169, v169
	v_add_u32_e32 v196, -3, v112
	v_add_u32_e32 v197, -4, v112
	v_add_u32_e32 v198, -5, v112
	v_cmp_gt_u32_e32 vcc, s91, v196
	v_cmp_gt_u32_e64 s[92:93], s91, v197
	v_cmp_gt_u32_e64 s[94:95], s91, v198
	v_cndmask_b32_e32 v167, 0, v167, vcc
	v_cndmask_b32_e64 v168, 0, v168, s[92:93]
	v_cndmask_b32_e64 v169, 0, v169, s[94:95]
	v_add_f32_e32 v103, v103, v167
	v_add_f32_e32 v103, v103, v168
	v_add_f32_e32 v103, v103, v169
	s_waitcnt lgkmcnt(5)
	v_sub_f32_e32 v170, v170, v82
	v_sub_f32_e32 v171, v171, v82
	v_sub_f32_e32 v172, v172, v82
	v_exp_f32_e32 v170, v170
	v_exp_f32_e32 v171, v171
	v_exp_f32_e32 v172, v172
	v_add_u32_e32 v196, -6, v112
	v_add_u32_e32 v197, -7, v112
	v_add_u32_e32 v198, -8, v112
	v_cmp_gt_u32_e32 vcc, s91, v196
	v_cmp_gt_u32_e64 s[92:93], s91, v197
	v_cmp_gt_u32_e64 s[94:95], s91, v198
	v_cndmask_b32_e32 v170, 0, v170, vcc
	v_cndmask_b32_e64 v171, 0, v171, s[92:93]
	v_cndmask_b32_e64 v172, 0, v172, s[94:95]
	v_add_f32_e32 v103, v103, v170
	v_add_f32_e32 v103, v103, v171
	v_add_f32_e32 v103, v103, v172
	v_sub_f32_e32 v173, v173, v82
	v_sub_f32_e32 v174, v174, v82
	v_sub_f32_e32 v175, v175, v82
	v_exp_f32_e32 v173, v173
	v_exp_f32_e32 v174, v174
	v_exp_f32_e32 v175, v175
	v_add_u32_e32 v196, -9, v112
	v_add_u32_e32 v197, -10, v112
	v_add_u32_e32 v198, -11, v112
	v_cmp_gt_u32_e32 vcc, s91, v196
	v_cmp_gt_u32_e64 s[92:93], s91, v197
	v_cmp_gt_u32_e64 s[94:95], s91, v198
	v_cndmask_b32_e32 v173, 0, v173, vcc
	v_cndmask_b32_e64 v174, 0, v174, s[92:93]
	v_cndmask_b32_e64 v175, 0, v175, s[94:95]
	v_add_f32_e32 v103, v103, v173
	v_add_f32_e32 v103, v103, v174
	v_add_f32_e32 v103, v103, v175
	s_waitcnt lgkmcnt(4)
	v_sub_f32_e32 v176, v176, v82
	v_sub_f32_e32 v177, v177, v82
	v_sub_f32_e32 v178, v178, v82
	v_exp_f32_e32 v176, v176
	v_exp_f32_e32 v177, v177
	v_exp_f32_e32 v178, v178
	v_add_u32_e32 v196, -12, v112
	v_add_u32_e32 v197, -13, v112
	v_add_u32_e32 v198, -14, v112
	v_cmp_gt_u32_e32 vcc, s91, v196
	v_cmp_gt_u32_e64 s[92:93], s91, v197
	v_cmp_gt_u32_e64 s[94:95], s91, v198
	v_cndmask_b32_e32 v176, 0, v176, vcc
	v_cndmask_b32_e64 v177, 0, v177, s[92:93]
	v_cndmask_b32_e64 v178, 0, v178, s[94:95]
	v_add_f32_e32 v103, v103, v176
	v_add_f32_e32 v103, v103, v177
	v_add_f32_e32 v103, v103, v178
	s_waitcnt lgkmcnt(3)
; __device__ __forceinline__ unsigned pack2(float a, float b) { return (unsigned)f2bf(a) | ((unsigned)f2bf(b) << 16); }
; template <int DH, int MODE>
; __device__ void attn_item(const Params& p, int layer, int b, int blk, int head, char* smem) {
;     ...
; #pragma unroll 2
;         for (int s8 = 0; s8 < 4; ++s8) {
;           float4 va = s4[2 * s8], vb = s4[2 * s8 + 1];
;           float e[8] = {va.x, va.y, va.z, va.w, vb.x, vb.y, vb.z, vb.w};
;           float pv[8];
; #pragma unroll
;           for (int k = 0; k < 8; ++k) {
;             int kj = kjb + s8 * 8 + k;
;             bool valid = (kj > row) && (kj <= row + 128);
;             float pe = valid ? __builtin_amdgcn_exp2f(e[k] - m_new) : 0.f;
;             pv[k] = pe;
;             psum += pe;
;           }
;           uint4 ov;
;           ov.x = pack2(pv[0], pv[1]); ov.y = pack2(pv[2], pv[3]);
;           ov.z = pack2(pv[4], pv[5]); ov.w = pack2(pv[6], pv[7]);
;           *reinterpret_cast<uint4*>(prow + s8 * 16) = ov;
;         }
;         psum += __shfl_xor(psum, 1);
;         l_run = l_run * alpha + psum;
;         m_run = m_new;
;         if (half == 0) alpha_s[row] = alpha;
	v_sub_f32_e32 v179, v179, v82
	v_sub_f32_e32 v180, v180, v82
	v_sub_f32_e32 v181, v181, v82
	v_exp_f32_e32 v179, v179
	v_exp_f32_e32 v180, v180
	v_exp_f32_e32 v181, v181
	v_add_u32_e32 v196, -15, v112
	v_add_u32_e32 v197, -16, v112
	v_add_u32_e32 v198, 0xffffffef, v112
	v_cmp_gt_u32_e32 vcc, s91, v196
	v_cmp_gt_u32_e64 s[92:93], s91, v197
	v_cmp_gt_u32_e64 s[94:95], s91, v198
	v_cndmask_b32_e32 v179, 0, v179, vcc
	v_cndmask_b32_e64 v180, 0, v180, s[92:93]
	v_cndmask_b32_e64 v181, 0, v181, s[94:95]
	v_add_f32_e32 v103, v103, v179
	v_add_f32_e32 v103, v103, v180
	v_add_f32_e32 v103, v103, v181
	s_waitcnt lgkmcnt(2)
	v_sub_f32_e32 v182, v182, v82
	v_sub_f32_e32 v183, v183, v82
	v_sub_f32_e32 v184, v184, v82
	v_exp_f32_e32 v182, v182
	v_exp_f32_e32 v183, v183
	v_exp_f32_e32 v184, v184
	v_add_u32_e32 v196, 0xffffffee, v112
	v_add_u32_e32 v197, 0xffffffed, v112
	v_add_u32_e32 v198, 0xffffffec, v112
	v_cmp_gt_u32_e32 vcc, s91, v196
	v_cmp_gt_u32_e64 s[92:93], s91, v197
	v_cmp_gt_u32_e64 s[94:95], s91, v198
	v_cndmask_b32_e32 v182, 0, v182, vcc
	v_cndmask_b32_e64 v183, 0, v183, s[92:93]
	v_cndmask_b32_e64 v184, 0, v184, s[94:95]
	v_add_f32_e32 v103, v103, v182
	v_add_f32_e32 v103, v103, v183
	v_add_f32_e32 v103, v103, v184
	v_sub_f32_e32 v185, v185, v82
	v_sub_f32_e32 v186, v186, v82
	v_sub_f32_e32 v187, v187, v82
	v_exp_f32_e32 v185, v185
	v_exp_f32_e32 v186, v186
	v_exp_f32_e32 v187, v187
	v_add_u32_e32 v196, 0xffffffeb, v112
	v_add_u32_e32 v197, 0xffffffea, v112
	v_add_u32_e32 v198, 0xffffffe9, v112
	v_cmp_gt_u32_e32 vcc, s91, v196
	v_cmp_gt_u32_e64 s[92:93], s91, v197
	v_cmp_gt_u32_e64 s[94:95], s91, v198
	v_cndmask_b32_e32 v185, 0, v185, vcc
	v_cndmask_b32_e64 v186, 0, v186, s[92:93]
	v_cndmask_b32_e64 v187, 0, v187, s[94:95]
	v_add_f32_e32 v103, v103, v185
	v_add_f32_e32 v103, v103, v186
	v_add_f32_e32 v103, v103, v187
	s_waitcnt lgkmcnt(1)
	v_sub_f32_e32 v188, v188, v82
	v_sub_f32_e32 v189, v189, v82
	v_sub_f32_e32 v190, v190, v82
	v_exp_f32_e32 v188, v188
	v_exp_f32_e32 v189, v189
	v_exp_f32_e32 v190, v190
	v_add_u32_e32 v196, 0xffffffe8, v112
	v_add_u32_e32 v197, 0xffffffe7, v112
	v_add_u32_e32 v198, 0xffffffe6, v112
	v_cmp_gt_u32_e32 vcc, s91, v196
	v_cmp_gt_u32_e64 s[92:93], s91, v197
	v_cmp_gt_u32_e64 s[94:95], s91, v198
	v_cndmask_b32_e32 v188, 0, v188, vcc
	v_cndmask_b32_e64 v189, 0, v189, s[92:93]
	v_cndmask_b32_e64 v190, 0, v190, s[94:95]
	v_add_f32_e32 v103, v103, v188
	v_add_f32_e32 v103, v103, v189
	v_add_f32_e32 v103, v103, v190
	s_waitcnt lgkmcnt(0)
	v_sub_f32_e32 v191, v191, v82
	v_sub_f32_e32 v192, v192, v82
	v_sub_f32_e32 v193, v193, v82
	v_exp_f32_e32 v191, v191
	v_exp_f32_e32 v192, v192
	v_exp_f32_e32 v193, v193
	v_add_u32_e32 v196, 0xffffffe5, v112
	v_add_u32_e32 v197, 0xffffffe4, v112
	v_add_u32_e32 v198, 0xffffffe3, v112
	v_cmp_gt_u32_e32 vcc, s91, v196
	v_cmp_gt_u32_e64 s[92:93], s91, v197
	v_cmp_gt_u32_e64 s[94:95], s91, v198
	v_cndmask_b32_e32 v191, 0, v191, vcc
	v_cndmask_b32_e64 v192, 0, v192, s[92:93]
	v_cndmask_b32_e64 v193, 0, v193, s[94:95]
	v_add_f32_e32 v103, v103, v191
	v_add_f32_e32 v103, v103, v192
	v_add_f32_e32 v103, v103, v193
	v_sub_f32_e32 v194, v194, v82
	v_sub_f32_e32 v195, v195, v82
	v_exp_f32_e32 v194, v194
	v_exp_f32_e32 v195, v195
	v_add_u32_e32 v196, 0xffffffe2, v112
	v_add_u32_e32 v197, 0xffffffe1, v112
	v_cmp_gt_u32_e32 vcc, s91, v196
	v_cmp_gt_u32_e64 s[92:93], s91, v197
	s_nop 0
	v_cndmask_b32_e32 v194, 0, v194, vcc
	v_cndmask_b32_e64 v195, 0, v195, s[92:93]
	v_add_f32_e32 v103, v103, v194
	v_add_f32_e32 v103, v103, v195
	v_cvt_pk_bf16_f32 v104, v164, v165
	v_cvt_pk_bf16_f32 v105, v166, v167
	v_cvt_pk_bf16_f32 v106, v168, v169
	v_cvt_pk_bf16_f32 v107, v170, v171
	ds_write_b128 v101, v[104:107]
	s_nop 0
	v_cvt_pk_bf16_f32 v104, v172, v173
	v_cvt_pk_bf16_f32 v105, v174, v175
	v_cvt_pk_bf16_f32 v106, v176, v177
	v_cvt_pk_bf16_f32 v107, v178, v179
	ds_write_b128 v101, v[104:107] offset:16
	s_nop 0
	v_cvt_pk_bf16_f32 v104, v180, v181
	v_cvt_pk_bf16_f32 v105, v182, v183
	v_cvt_pk_bf16_f32 v106, v184, v185
	v_cvt_pk_bf16_f32 v107, v186, v187
	ds_write_b128 v101, v[104:107] offset:32
	s_nop 0
	v_cvt_pk_bf16_f32 v104, v188, v189
	v_cvt_pk_bf16_f32 v105, v190, v191
	v_cvt_pk_bf16_f32 v106, v192, v193
	v_cvt_pk_bf16_f32 v107, v194, v195
	ds_write_b128 v101, v[104:107] offset:48
	v_sub_f32_e32 v101, v87, v82
	ds_bpermute_b32 v87, v83, v103
	v_exp_f32_e32 v83, v101
	s_and_saveexec_b64 s[14:15], s[12:13]
	ds_write_b32 v97, v83 offset:8192
	s_or_b64 exec, exec, s[14:15]
	s_waitcnt lgkmcnt(0)
	v_add_f32_e32 v101, v103, v87
	v_fmac_f32_e32 v101, v88, v83
	v_mov_b32_e32 v87, v82
	v_mov_b32_e32 v88, v101

; template <int DH, int MODE>
; __device__ void attn_item(const Params& p, int layer, int b, int blk, int head, char* smem) {
;     ...
;     __syncthreads();
;     V_SCATTER_(vr0, 0);
;     V_SCATTER_(vr1, 1);
;     if (KCH > 2) {
;       V_SCATTER_(vr2, 2);
;       V_SCATTER_(vr3, 3);
;     }
;     KV_LOAD_(it + 1);
;     if (!wskip) {
;       float4* s4 = reinterpret_cast<float4*>(Sf + row * SSTR + half * 32);
;       char* prow = Pb + half * 8192 + row * 64;
;       if (MODE == 0) {
;         const int kjb = kj0 + half * 32;
;         float tmax = -1e30f;
; #pragma unroll
;         for (int c = 0; c < 8; ++c) {
;           float4 v = s4[c];
;           float e[4] = {v.x, v.y, v.z, v.w};
; #pragma unroll
;           for (int k = 0; k < 4; ++k) {
;             int kj = kjb + c * 4 + k;
;             bool valid = (kj > row) && (kj <= row + 128);
;             tmax = valid ? fmaxf(tmax, e[k]) : tmax;
;           }
;         }
.LBB0_1129:
	s_or_b64 exec, exec, s[8:9]
	s_add_i32 s82, s82, 1
	s_min_i32 s8, s82, s80
	s_add_i32 s8, s8, s79
	s_lshl_b32 s8, s8, 6
	s_add_i32 s8, s8, s81
	s_ashr_i32 s9, s8, 31
	s_add_u32 s8, s8, s77
	s_addc_u32 s9, s9, 0
	s_waitcnt lgkmcnt(0)
	s_barrier
	ds_write_b16 v96, v48
	ds_write_b16_d16_hi v96, v48 offset:64
	ds_write_b16 v96, v49 offset:128
	ds_write_b16_d16_hi v96, v49 offset:192
	ds_write_b16 v96, v50 offset:256
	ds_write_b16_d16_hi v96, v50 offset:320
	ds_write_b16 v96, v51 offset:384
	ds_write_b16_d16_hi v96, v51 offset:448
	s_waitcnt vmcnt(0)
	ds_write_b16 v96, v52 offset:2048
	ds_write_b16_d16_hi v96, v52 offset:2112
	ds_write_b16 v96, v53 offset:2176
	ds_write_b16_d16_hi v96, v53 offset:2240
	ds_write_b16 v96, v54 offset:2304
	ds_write_b16_d16_hi v96, v54 offset:2368
	ds_write_b16 v96, v55 offset:2432
	ds_write_b16_d16_hi v96, v55 offset:2496
	v_lshl_add_u64 v[48:49], s[8:9], 0, v[66:67]
	v_mad_u64_u32 v[52:53], s[12:13], v48, s39, v[76:77]
	v_or_b32_e32 v48, s8, v72
	v_mad_i32_i24 v53, v49, s39, v53
	v_mad_u64_u32 v[54:55], s[12:13], v48, s39, v[78:79]
	v_add_co_u32_e32 v48, vcc, 0x4c000, v52
	v_mad_i32_i24 v55, s9, v160, v55
	s_nop 0
	v_addc_co_u32_e32 v49, vcc, 0, v53, vcc
	global_load_dwordx4 v[60:63], v[48:49], off
	s_nop 0
	global_load_dwordx4 v[48:51], v[54:55], off
	global_load_dwordx4 v[56:59], v[52:53], off
	s_nop 0
	global_load_dwordx4 v[52:55], v[54:55], off offset:64
	s_and_saveexec_b64 s[46:47], s[44:45]
	s_cbranch_execz .LBB0_1151
	v_or_b32_e32 v101, s10, v89
	s_movk_i32 s91, 0x80
	ds_read_b128 v[164:167], v90 offset:16384
	ds_read_b128 v[168:171], v90 offset:16400
	ds_read_b128 v[172:175], v90 offset:16416
	ds_read_b128 v[176:179], v90 offset:16432
	ds_read_b128 v[180:183], v90 offset:16448
	ds_read_b128 v[184:187], v90 offset:16464
	ds_read_b128 v[188:191], v90 offset:16480
	ds_read_b128 v[192:195], v90 offset:16496
	v_sub_u32_e32 v102, v80, v101
	v_mov_b32_e32 v83, 0xf149f2ca
	v_mov_b32_e32 v196, v102
	v_add_u32_e32 v197, -1, v102
	v_add_u32_e32 v198, -2, v102
	v_cmp_gt_u32_e32 vcc, s91, v196
	v_cmp_gt_u32_e64 s[92:93], s91, v197
	v_cmp_gt_u32_e64 s[94:95], s91, v198
	s_waitcnt lgkmcnt(7)
	v_cndmask_b32_e32 v164, v83, v164, vcc
	v_cndmask_b32_e64 v165, v83, v165, s[92:93]
	v_cndmask_b32_e64 v166, v83, v166, s[94:95]
	v_add_u32_e32 v196, -3, v102
	v_add_u32_e32 v197, -4, v102
	v_add_u32_e32 v198, -5, v102
	v_cmp_gt_u32_e32 vcc, s91, v196
	v_cmp_gt_u32_e64 s[92:93], s91, v197
	v_cmp_gt_u32_e64 s[94:95], s91, v198
	s_waitcnt lgkmcnt(6)
	v_cndmask_b32_e32 v167, v83, v167, vcc
	v_cndmask_b32_e64 v168, v83, v168, s[92:93]
	v_cndmask_b32_e64 v169, v83, v169, s[94:95]
	v_add_u32_e32 v196, -6, v102
	v_add_u32_e32 v197, -7, v102
	v_add_u32_e32 v198, -8, v102
	v_cmp_gt_u32_e32 vcc, s91, v196
	v_cmp_gt_u32_e64 s[92:93], s91, v197
	v_cmp_gt_u32_e64 s[94:95], s91, v198
	s_waitcnt lgkmcnt(5)
	v_cndmask_b32_e32 v170, v83, v170, vcc
	v_cndmask_b32_e64 v171, v83, v171, s[92:93]
	v_cndmask_b32_e64 v172, v83, v172, s[94:95]
	v_add_u32_e32 v196, -9, v102
	v_add_u32_e32 v197, -10, v102
	v_add_u32_e32 v198, -11, v102
	v_cmp_gt_u32_e32 vcc, s91, v196
	v_cmp_gt_u32_e64 s[92:93], s91, v197
	v_cmp_gt_u32_e64 s[94:95], s91, v198
	v_cndmask_b32_e32 v173, v83, v173, vcc
	v_cndmask_b32_e64 v174, v83, v174, s[92:93]
	v_cndmask_b32_e64 v175, v83, v175, s[94:95]
	v_add_u32_e32 v196, -12, v102
	v_add_u32_e32 v197, -13, v102
	v_add_u32_e32 v198, -14, v102
	v_cmp_gt_u32_e32 vcc, s91, v196
	v_cmp_gt_u32_e64 s[92:93], s91, v197
	v_cmp_gt_u32_e64 s[94:95], s91, v198
	s_waitcnt lgkmcnt(4)
	v_cndmask_b32_e32 v176, v83, v176, vcc
	v_cndmask_b32_e64 v177, v83, v177, s[92:93]
	v_cndmask_b32_e64 v178, v83, v178, s[94:95]
	v_add_u32_e32 v196, -15, v102
	v_add_u32_e32 v197, -16, v102
	v_add_u32_e32 v198, 0xffffffef, v102
	v_cmp_gt_u32_e32 vcc, s91, v196
	v_cmp_gt_u32_e64 s[92:93], s91, v197
	v_cmp_gt_u32_e64 s[94:95], s91, v198
	s_waitcnt lgkmcnt(3)
	v_cndmask_b32_e32 v179, v83, v179, vcc
	v_cndmask_b32_e64 v180, v83, v180, s[92:93]
	v_cndmask_b32_e64 v181, v83, v181, s[94:95]
	v_add_u32_e32 v196, 0xffffffee, v102
	v_add_u32_e32 v197, 0xffffffed, v102
	v_add_u32_e32 v198, 0xffffffec, v102
	v_cmp_gt_u32_e32 vcc, s91, v196
	v_cmp_gt_u32_e64 s[92:93], s91, v197
	v_cmp_gt_u32_e64 s[94:95], s91, v198
	s_waitcnt lgkmcnt(2)
	v_cndmask_b32_e32 v182, v83, v182, vcc
	v_cndmask_b32_e64 v183, v83, v183, s[92:93]
	v_cndmask_b32_e64 v184, v83, v184, s[94:95]
	v_add_u32_e32 v196, 0xffffffeb, v102
	v_add_u32_e32 v197, 0xffffffea, v102
	v_add_u32_e32 v198, 0xffffffe9, v102
	v_cmp_gt_u32_e32 vcc, s91, v196
	v_cmp_gt_u32_e64 s[92:93], s91, v197
	v_cmp_gt_u32_e64 s[94:95], s91, v198
	v_cndmask_b32_e32 v185, v83, v185, vcc
	v_cndmask_b32_e64 v186, v83, v186, s[92:93]
	v_cndmask_b32_e64 v187, v83, v187, s[94:95]
	v_add_u32_e32 v196, 0xffffffe8, v102
	v_add_u32_e32 v197, 0xffffffe7, v102
	v_add_u32_e32 v198, 0xffffffe6, v102
	v_cmp_gt_u32_e32 vcc, s91, v196
	v_cmp_gt_u32_e64 s[92:93], s91, v197
	v_cmp_gt_u32_e64 s[94:95], s91, v198
	s_waitcnt lgkmcnt(1)
	v_cndmask_b32_e32 v188, v83, v188, vcc
	v_cndmask_b32_e64 v189, v83, v189, s[92:93]
	v_cndmask_b32_e64 v190, v83, v190, s[94:95]
	v_add_u32_e32 v196, 0xffffffe5, v102
	v_add_u32_e32 v197, 0xffffffe4, v102
	v_add_u32_e32 v198, 0xffffffe3, v102
	v_cmp_gt_u32_e32 vcc, s91, v196
	v_cmp_gt_u32_e64 s[92:93], s91, v197
	v_cmp_gt_u32_e64 s[94:95], s91, v198
	s_waitcnt lgkmcnt(0)
; template <int DH, int MODE>
; __device__ void attn_item(const Params& p, int layer, int b, int blk, int head, char* smem) {
;     ...
; #pragma unroll
;         for (int c = 0; c < 8; ++c) {
;           float4 v = s4[c];
;           float e[4] = {v.x, v.y, v.z, v.w};
; #pragma unroll
;           for (int k = 0; k < 4; ++k) {
;             int kj = kjb + c * 4 + k;
;             bool valid = (kj > row) && (kj <= row + 128);
;             tmax = valid ? fmaxf(tmax, e[k]) : tmax;
;           }
;         }
;         tmax = fmaxf(tmax, __shfl_xor(tmax, 1));
;         float m_new = fmaxf(m_run, tmax);
;         float alpha = __builtin_amdgcn_exp2f(m_run - m_new);
;         float psum = 0.f;
; #pragma unroll 2
;         for (int s8 = 0; s8 < 4; ++s8) {
;           float4 va = s4[2 * s8], vb = s4[2 * s8 + 1];
;           float e[8] = {va.x, va.y, va.z, va.w, vb.x, vb.y, vb.z, vb.w};
;           float pv[8];
; #pragma unroll
;           for (int k = 0; k < 8; ++k) {
;             int kj = kjb + s8 * 8 + k;
;             bool valid = (kj > row) && (kj <= row + 128);
;             float pe = valid ? __builtin_amdgcn_exp2f(e[k] - m_new) : 0.f;
;             pv[k] = pe;
;             psum += pe;
;           }
	v_cndmask_b32_e32 v191, v83, v191, vcc
	v_cndmask_b32_e64 v192, v83, v192, s[92:93]
	v_cndmask_b32_e64 v193, v83, v193, s[94:95]
	v_add_u32_e32 v196, 0xffffffe2, v102
	v_add_u32_e32 v197, 0xffffffe1, v102
	v_cmp_gt_u32_e32 vcc, s91, v196
	v_cmp_gt_u32_e64 s[92:93], s91, v197
	s_nop 0
	v_cndmask_b32_e32 v194, v83, v194, vcc
	v_cndmask_b32_e64 v195, v83, v195, s[92:93]
	v_max3_f32 v164, v164, v165, v166
	v_max3_f32 v167, v167, v168, v169
	v_max3_f32 v170, v170, v171, v172
	v_max3_f32 v173, v173, v174, v175
	v_max3_f32 v176, v176, v177, v178
	v_max3_f32 v179, v179, v180, v181
	v_max3_f32 v182, v182, v183, v184
	v_max3_f32 v185, v185, v186, v187
	v_max3_f32 v188, v188, v189, v190
	v_max3_f32 v191, v191, v192, v193
	v_max_f32_e32 v194, v194, v195
	v_max3_f32 v164, v164, v167, v170
	v_max3_f32 v173, v173, v176, v179
	v_max3_f32 v182, v182, v185, v188
	v_max_f32_e32 v191, v191, v194
	v_max3_f32 v164, v164, v173, v182
	v_max_f32_e32 v164, v164, v191
	v_mov_b32_e32 v82, v164
	v_cmp_lt_i32_e32 vcc, v157, v158
	s_mov_b32 s83, 0
	v_mov_b32_e32 v103, 0
	v_cndmask_b32_e32 v83, v156, v157, vcc
	v_lshlrev_b32_e32 v83, 2, v83
	ds_bpermute_b32 v101, v83, v82
	v_mov_b32_e32 v102, v91
	s_waitcnt lgkmcnt(0)
	v_max3_f32 v82, v87, v82, v101
	v_mov_b32_e32 v101, v93
	ds_read_b128 v[164:167], v102
	ds_read_b128 v[168:171], v102 offset:16
	ds_read_b128 v[172:175], v102 offset:32
	ds_read_b128 v[176:179], v102 offset:48
	ds_read_b128 v[180:183], v102 offset:64
	ds_read_b128 v[184:187], v102 offset:80
	ds_read_b128 v[188:191], v102 offset:96
	ds_read_b128 v[192:195], v102 offset:112
	s_movk_i32 s91, 0x80
	v_sub_u32_e32 v112, v80, v92
	s_waitcnt lgkmcnt(7)
	v_sub_f32_e32 v164, v164, v82
	v_sub_f32_e32 v165, v165, v82
	v_sub_f32_e32 v166, v166, v82
	v_exp_f32_e32 v164, v164
	v_exp_f32_e32 v165, v165
	v_exp_f32_e32 v166, v166
	v_mov_b32_e32 v196, v112
	v_add_u32_e32 v197, -1, v112
	v_add_u32_e32 v198, -2, v112
	v_cmp_gt_u32_e32 vcc, s91, v196
	v_cmp_gt_u32_e64 s[92:93], s91, v197
	v_cmp_gt_u32_e64 s[94:95], s91, v198
	v_cndmask_b32_e32 v164, 0, v164, vcc
	v_cndmask_b32_e64 v165, 0, v165, s[92:93]
	v_cndmask_b32_e64 v166, 0, v166, s[94:95]
	v_add_f32_e32 v103, v103, v164
	v_add_f32_e32 v103, v103, v165
	v_add_f32_e32 v103, v103, v166
	s_waitcnt lgkmcnt(6)
	v_sub_f32_e32 v167, v167, v82
	v_sub_f32_e32 v168, v168, v82
	v_sub_f32_e32 v169, v169, v82
	v_exp_f32_e32 v167, v167
	v_exp_f32_e32 v168, v168
	v_exp_f32_e32 v169, v169
	v_add_u32_e32 v196, -3, v112
	v_add_u32_e32 v197, -4, v112
	v_add_u32_e32 v198, -5, v112
	v_cmp_gt_u32_e32 vcc, s91, v196
	v_cmp_gt_u32_e64 s[92:93], s91, v197
	v_cmp_gt_u32_e64 s[94:95], s91, v198
	v_cndmask_b32_e32 v167, 0, v167, vcc
	v_cndmask_b32_e64 v168, 0, v168, s[92:93]
	v_cndmask_b32_e64 v169, 0, v169, s[94:95]
	v_add_f32_e32 v103, v103, v167
	v_add_f32_e32 v103, v103, v168
	v_add_f32_e32 v103, v103, v169
	s_waitcnt lgkmcnt(5)
	v_sub_f32_e32 v170, v170, v82
	v_sub_f32_e32 v171, v171, v82
	v_sub_f32_e32 v172, v172, v82
	v_exp_f32_e32 v170, v170
	v_exp_f32_e32 v171, v171
	v_exp_f32_e32 v172, v172
	v_add_u32_e32 v196, -6, v112
	v_add_u32_e32 v197, -7, v112
	v_add_u32_e32 v198, -8, v112
	v_cmp_gt_u32_e32 vcc, s91, v196
	v_cmp_gt_u32_e64 s[92:93], s91, v197
	v_cmp_gt_u32_e64 s[94:95], s91, v198
	v_cndmask_b32_e32 v170, 0, v170, vcc
	v_cndmask_b32_e64 v171, 0, v171, s[92:93]
	v_cndmask_b32_e64 v172, 0, v172, s[94:95]
	v_add_f32_e32 v103, v103, v170
	v_add_f32_e32 v103, v103, v171
	v_add_f32_e32 v103, v103, v172
	v_sub_f32_e32 v173, v173, v82
	v_sub_f32_e32 v174, v174, v82
	v_sub_f32_e32 v175, v175, v82
	v_exp_f32_e32 v173, v173
	v_exp_f32_e32 v174, v174
	v_exp_f32_e32 v175, v175
	v_add_u32_e32 v196, -9, v112
	v_add_u32_e32 v197, -10, v112
	v_add_u32_e32 v198, -11, v112
	v_cmp_gt_u32_e32 vcc, s91, v196
	v_cmp_gt_u32_e64 s[92:93], s91, v197
	v_cmp_gt_u32_e64 s[94:95], s91, v198
	v_cndmask_b32_e32 v173, 0, v173, vcc
	v_cndmask_b32_e64 v174, 0, v174, s[92:93]
	v_cndmask_b32_e64 v175, 0, v175, s[94:95]
	v_add_f32_e32 v103, v103, v173
	v_add_f32_e32 v103, v103, v174
	v_add_f32_e32 v103, v103, v175
	s_waitcnt lgkmcnt(4)
	v_sub_f32_e32 v176, v176, v82
	v_sub_f32_e32 v177, v177, v82
	v_sub_f32_e32 v178, v178, v82
	v_exp_f32_e32 v176, v176
	v_exp_f32_e32 v177, v177
	v_exp_f32_e32 v178, v178
	v_add_u32_e32 v196, -12, v112
	v_add_u32_e32 v197, -13, v112
	v_add_u32_e32 v198, -14, v112
	v_cmp_gt_u32_e32 vcc, s91, v196
	v_cmp_gt_u32_e64 s[92:93], s91, v197
	v_cmp_gt_u32_e64 s[94:95], s91, v198
	v_cndmask_b32_e32 v176, 0, v176, vcc
	v_cndmask_b32_e64 v177, 0, v177, s[92:93]
	v_cndmask_b32_e64 v178, 0, v178, s[94:95]
	v_add_f32_e32 v103, v103, v176
	v_add_f32_e32 v103, v103, v177
	v_add_f32_e32 v103, v103, v178
	s_waitcnt lgkmcnt(3)
; __device__ __forceinline__ unsigned pack2(float a, float b) { return (unsigned)f2bf(a) | ((unsigned)f2bf(b) << 16); }
; template <int DH, int MODE>
; __device__ void attn_item(const Params& p, int layer, int b, int blk, int head, char* smem) {
;     ...
; #pragma unroll 2
;         for (int s8 = 0; s8 < 4; ++s8) {
;           float4 va = s4[2 * s8], vb = s4[2 * s8 + 1];
;           float e[8] = {va.x, va.y, va.z, va.w, vb.x, vb.y, vb.z, vb.w};
;           float pv[8];
; #pragma unroll
;           for (int k = 0; k < 8; ++k) {
;             int kj = kjb + s8 * 8 + k;
;             bool valid = (kj > row) && (kj <= row + 128);
;             float pe = valid ? __builtin_amdgcn_exp2f(e[k] - m_new) : 0.f;
;             pv[k] = pe;
;             psum += pe;
;           }
;           uint4 ov;
;           ov.x = pack2(pv[0], pv[1]); ov.y = pack2(pv[2], pv[3]);
;           ov.z = pack2(pv[4], pv[5]); ov.w = pack2(pv[6], pv[7]);
;           *reinterpret_cast<uint4*>(prow + s8 * 16) = ov;
;         }
;         psum += __shfl_xor(psum, 1);
;         l_run = l_run * alpha + psum;
;         m_run = m_new;
;         if (half == 0) alpha_s[row] = alpha;
	v_sub_f32_e32 v179, v179, v82
	v_sub_f32_e32 v180, v180, v82
	v_sub_f32_e32 v181, v181, v82
	v_exp_f32_e32 v179, v179
	v_exp_f32_e32 v180, v180
	v_exp_f32_e32 v181, v181
	v_add_u32_e32 v196, -15, v112
	v_add_u32_e32 v197, -16, v112
	v_add_u32_e32 v198, 0xffffffef, v112
	v_cmp_gt_u32_e32 vcc, s91, v196
	v_cmp_gt_u32_e64 s[92:93], s91, v197
	v_cmp_gt_u32_e64 s[94:95], s91, v198
	v_cndmask_b32_e32 v179, 0, v179, vcc
	v_cndmask_b32_e64 v180, 0, v180, s[92:93]
	v_cndmask_b32_e64 v181, 0, v181, s[94:95]
	v_add_f32_e32 v103, v103, v179
	v_add_f32_e32 v103, v103, v180
	v_add_f32_e32 v103, v103, v181
	s_waitcnt lgkmcnt(2)
	v_sub_f32_e32 v182, v182, v82
	v_sub_f32_e32 v183, v183, v82
	v_sub_f32_e32 v184, v184, v82
	v_exp_f32_e32 v182, v182
	v_exp_f32_e32 v183, v183
	v_exp_f32_e32 v184, v184
	v_add_u32_e32 v196, 0xffffffee, v112
	v_add_u32_e32 v197, 0xffffffed, v112
	v_add_u32_e32 v198, 0xffffffec, v112
	v_cmp_gt_u32_e32 vcc, s91, v196
	v_cmp_gt_u32_e64 s[92:93], s91, v197
	v_cmp_gt_u32_e64 s[94:95], s91, v198
	v_cndmask_b32_e32 v182, 0, v182, vcc
	v_cndmask_b32_e64 v183, 0, v183, s[92:93]
	v_cndmask_b32_e64 v184, 0, v184, s[94:95]
	v_add_f32_e32 v103, v103, v182
	v_add_f32_e32 v103, v103, v183
	v_add_f32_e32 v103, v103, v184
	v_sub_f32_e32 v185, v185, v82
	v_sub_f32_e32 v186, v186, v82
	v_sub_f32_e32 v187, v187, v82
	v_exp_f32_e32 v185, v185
	v_exp_f32_e32 v186, v186
	v_exp_f32_e32 v187, v187
	v_add_u32_e32 v196, 0xffffffeb, v112
	v_add_u32_e32 v197, 0xffffffea, v112
	v_add_u32_e32 v198, 0xffffffe9, v112
	v_cmp_gt_u32_e32 vcc, s91, v196
	v_cmp_gt_u32_e64 s[92:93], s91, v197
	v_cmp_gt_u32_e64 s[94:95], s91, v198
	v_cndmask_b32_e32 v185, 0, v185, vcc
	v_cndmask_b32_e64 v186, 0, v186, s[92:93]
	v_cndmask_b32_e64 v187, 0, v187, s[94:95]
	v_add_f32_e32 v103, v103, v185
	v_add_f32_e32 v103, v103, v186
	v_add_f32_e32 v103, v103, v187
	s_waitcnt lgkmcnt(1)
	v_sub_f32_e32 v188, v188, v82
	v_sub_f32_e32 v189, v189, v82
	v_sub_f32_e32 v190, v190, v82
	v_exp_f32_e32 v188, v188
	v_exp_f32_e32 v189, v189
	v_exp_f32_e32 v190, v190
	v_add_u32_e32 v196, 0xffffffe8, v112
	v_add_u32_e32 v197, 0xffffffe7, v112
	v_add_u32_e32 v198, 0xffffffe6, v112
	v_cmp_gt_u32_e32 vcc, s91, v196
	v_cmp_gt_u32_e64 s[92:93], s91, v197
	v_cmp_gt_u32_e64 s[94:95], s91, v198
	v_cndmask_b32_e32 v188, 0, v188, vcc
	v_cndmask_b32_e64 v189, 0, v189, s[92:93]
	v_cndmask_b32_e64 v190, 0, v190, s[94:95]
	v_add_f32_e32 v103, v103, v188
	v_add_f32_e32 v103, v103, v189
	v_add_f32_e32 v103, v103, v190
	s_waitcnt lgkmcnt(0)
	v_sub_f32_e32 v191, v191, v82
	v_sub_f32_e32 v192, v192, v82
	v_sub_f32_e32 v193, v193, v82
	v_exp_f32_e32 v191, v191
	v_exp_f32_e32 v192, v192
	v_exp_f32_e32 v193, v193
	v_add_u32_e32 v196, 0xffffffe5, v112
	v_add_u32_e32 v197, 0xffffffe4, v112
	v_add_u32_e32 v198, 0xffffffe3, v112
	v_cmp_gt_u32_e32 vcc, s91, v196
	v_cmp_gt_u32_e64 s[92:93], s91, v197
	v_cmp_gt_u32_e64 s[94:95], s91, v198
	v_cndmask_b32_e32 v191, 0, v191, vcc
	v_cndmask_b32_e64 v192, 0, v192, s[92:93]
	v_cndmask_b32_e64 v193, 0, v193, s[94:95]
	v_add_f32_e32 v103, v103, v191
	v_add_f32_e32 v103, v103, v192
	v_add_f32_e32 v103, v103, v193
	v_sub_f32_e32 v194, v194, v82
	v_sub_f32_e32 v195, v195, v82
	v_exp_f32_e32 v194, v194
	v_exp_f32_e32 v195, v195
	v_add_u32_e32 v196, 0xffffffe2, v112
	v_add_u32_e32 v197, 0xffffffe1, v112
	v_cmp_gt_u32_e32 vcc, s91, v196
	v_cmp_gt_u32_e64 s[92:93], s91, v197
	s_nop 0
	v_cndmask_b32_e32 v194, 0, v194, vcc
	v_cndmask_b32_e64 v195, 0, v195, s[92:93]
	v_add_f32_e32 v103, v103, v194
	v_add_f32_e32 v103, v103, v195
	v_cvt_pk_bf16_f32 v104, v164, v165
	v_cvt_pk_bf16_f32 v105, v166, v167
	v_cvt_pk_bf16_f32 v106, v168, v169
	v_cvt_pk_bf16_f32 v107, v170, v171
	ds_write_b128 v101, v[104:107]
	s_nop 0
	v_cvt_pk_bf16_f32 v104, v172, v173
	v_cvt_pk_bf16_f32 v105, v174, v175
	v_cvt_pk_bf16_f32 v106, v176, v177
	v_cvt_pk_bf16_f32 v107, v178, v179
	ds_write_b128 v101, v[104:107] offset:16
	s_nop 0
	v_cvt_pk_bf16_f32 v104, v180, v181
	v_cvt_pk_bf16_f32 v105, v182, v183
	v_cvt_pk_bf16_f32 v106, v184, v185
	v_cvt_pk_bf16_f32 v107, v186, v187
	ds_write_b128 v101, v[104:107] offset:32
	s_nop 0
	v_cvt_pk_bf16_f32 v104, v188, v189
	v_cvt_pk_bf16_f32 v105, v190, v191
	v_cvt_pk_bf16_f32 v106, v192, v193
	v_cvt_pk_bf16_f32 v107, v194, v195
	ds_write_b128 v101, v[104:107] offset:48
	v_sub_f32_e32 v101, v87, v82
	ds_bpermute_b32 v87, v83, v103
	v_exp_f32_e32 v83, v101
	s_and_saveexec_b64 s[8:9], s[6:7]
	ds_write_b32 v97, v83 offset:8192
	s_or_b64 exec, exec, s[8:9]
	s_waitcnt lgkmcnt(0)
	v_add_f32_e32 v101, v103, v87
	v_fmac_f32_e32 v101, v88, v83
	v_mov_b32_e32 v87, v82
	v_mov_b32_e32 v88, v101
